# write-through (sc1) 16B stores in both GEMM epilogues so the grid barrier's L2 write-back has little dirty data left
# baseline (speedup 1.0000x reference)
; __device__ __forceinline__ unsigned cvt_pk_bf16(float lo, float hi) { unsigned r; asm volatile("v_cvt_pk_bf16_f32 %0, %1, %2" : "=v"(r) : "v"(lo), "v"(hi)); return r; }
;     __device__ __forceinline__ void operator()(const f32x4 (&acc)[2][2][4][2], const Unit& u, int wr, int wc, int fr, int fq) const {
;         const int row0 = u.pm * BM + wr * 64 + fr, col0 = u.pn * BM + wc * 32 + 4 * fq;
;         f32x4 bs[2][4];
; #pragma unroll
;         for (int q = 0; q < 4; ++q) bs[0][q] = *(const f32x4*)(xin + (size_t)row0 * ldc + col0 + (q >> 1) * HALF + (q & 1) * 16);
; #pragma unroll
;         for (int gi = 0; gi < 8; ++gi) {
;             const int ai = gi >> 2, m = gi & 3;
;             const int row = row0 + ai * HALF + m * 16;
;             const size_t off = (size_t)row * ldc + col0;
;             if (gi + 1 < 8) {
;                 const size_t offn = (size_t)(row0 + ((gi + 1) >> 2) * HALF + ((gi + 1) & 3) * 16) * ldc + col0;
; #pragma unroll
;                 for (int q = 0; q < 4; ++q) bs[(gi + 1) & 1][q] = *(const f32x4*)(xin + offn + (q >> 1) * HALF + (q & 1) * 16);
;             }
;             float sq = 0.f;
; #pragma unroll
;             for (int q = 0; q < 4; ++q) {
;                 const int bj = q >> 1, n = q & 1;
;                 const f32x4 o = bs[gi & 1][q] + acc[ai][bj][m][n];
;                 *(f32x4*)(out + off + bj * HALF + n * 16) = o;
;                 if (ss) {
;                     u32x2 w; w.x = cvt_pk_bf16(o[0], o[1]); w.y = cvt_pk_bf16(o[2], o[3]);
;                     *(u32x2*)(xb + off + bj * HALF + n * 16) = w;
;                     sq += (o[0] * o[0] + o[1] * o[1]) + (o[2] * o[2] + o[3] * o[3]);
;                 }
;             }
;             if (ss) { sq += __shfl_xor(sq, 16); sq += __shfl_xor(sq, 32); if (fq == 0) ss[(size_t)row * 32 + u.pn * 4 + wc] = sq; }
;         }
.LBB0_345:
	s_andn2_b64 vcc, exec, s[26:27]
	s_cbranch_vccnz .Lres_noss
	v_lshl_add_u32 v246, s55, 8, v188
	v_lshl_or_b32 v247, s2, 8, v190
	v_lshlrev_b32_e32 v247, 2, v247
	v_lshl_add_u32 v160, v246, 13, v247
	v_add_u32_e32 v161, 0x20000, v160
	v_add_u32_e32 v162, 0x40000, v160
	v_add_u32_e32 v163, 0x60000, v160
	v_add_u32_e32 v164, 0x100000, v160
	v_add_u32_e32 v165, 0x120000, v160
	v_add_u32_e32 v192, 0x140000, v160
	v_add_u32_e32 v193, 0x160000, v160
	s_lshl_b32 s34, s2, 4
	s_lshl_b32 s35, s46, 2
	s_add_i32 s34, s34, s35
	v_lshl_add_u32 v189, v246, 7, s34
	v_and_b32_e32 v246, 8, v188
	v_mov_b32_e32 v247, 0x10040
	v_cmp_eq_u32_e32 vcc, 0, v246
	v_mov_b32_e32 v246, 0xffff0040
	s_nop 0
	v_cndmask_b32_e32 v234, v246, v169, vcc
	v_cndmask_b32_e32 v235, 0, v247, vcc
	v_add_u32_e32 v236, v160, v234
	v_add_u32_e32 v237, v160, v235
	global_load_dwordx4 v[128:131], v236, s[14:15]
	global_load_dwordx4 v[132:135], v237, s[14:15]
	global_load_dwordx4 v[136:139], v236, s[14:15] offset:512
	global_load_dwordx4 v[140:143], v237, s[14:15] offset:512
	v_add_u32_e32 v236, v161, v234
	v_add_u32_e32 v237, v161, v235
	global_load_dwordx4 v[144:147], v236, s[14:15]
	global_load_dwordx4 v[148:151], v237, s[14:15]
	global_load_dwordx4 v[152:155], v236, s[14:15] offset:512
	global_load_dwordx4 v[156:159], v237, s[14:15] offset:512
	v_add_u32_e32 v236, v162, v234
	v_add_u32_e32 v237, v162, v235
	global_load_dwordx4 v[206:209], v236, s[14:15]
	global_load_dwordx4 v[210:213], v237, s[14:15]
	global_load_dwordx4 v[214:217], v236, s[14:15] offset:512
	global_load_dwordx4 v[218:221], v237, s[14:15] offset:512
	v_and_b32_e32 v245, 4, v190
	v_mul_u32_u24_e32 v245, 6, v245
	s_waitcnt vmcnt(8)
	v_mov_b32_dpp v222, v128 row_ror:8 row_mask:0xf bank_mask:0xf
	v_mov_b32_dpp v223, v129 row_ror:8 row_mask:0xf bank_mask:0xf
	v_mov_b32_dpp v224, v130 row_ror:8 row_mask:0xf bank_mask:0xf
	v_mov_b32_dpp v225, v131 row_ror:8 row_mask:0xf bank_mask:0xf
	v_mov_b32_dpp v226, v132 row_ror:8 row_mask:0xf bank_mask:0xf
	v_mov_b32_dpp v227, v133 row_ror:8 row_mask:0xf bank_mask:0xf
	v_mov_b32_dpp v228, v134 row_ror:8 row_mask:0xf bank_mask:0xf
	v_mov_b32_dpp v229, v135 row_ror:8 row_mask:0xf bank_mask:0xf
	v_cndmask_b32_e32 v230, v132, v128, vcc
	v_cndmask_b32_e32 v231, v133, v129, vcc
	v_cndmask_b32_e32 v232, v134, v130, vcc
	v_cndmask_b32_e32 v233, v135, v131, vcc
	v_cndmask_b32_e32 v222, v226, v222, vcc
	v_cndmask_b32_e32 v223, v227, v223, vcc
	v_cndmask_b32_e32 v224, v228, v224, vcc
	v_cndmask_b32_e32 v225, v229, v225, vcc
	v_pk_add_f32 v[124:125], v[230:231], v[124:125]
	v_pk_add_f32 v[126:127], v[232:233], v[126:127]
	v_pk_add_f32 v[120:121], v[222:223], v[120:121]
	v_pk_add_f32 v[122:123], v[224:225], v[122:123]
	v_mov_b32_dpp v222, v136 row_ror:8 row_mask:0xf bank_mask:0xf
	v_mov_b32_dpp v223, v137 row_ror:8 row_mask:0xf bank_mask:0xf
	v_mov_b32_dpp v224, v138 row_ror:8 row_mask:0xf bank_mask:0xf
	v_mov_b32_dpp v225, v139 row_ror:8 row_mask:0xf bank_mask:0xf
	v_mov_b32_dpp v226, v140 row_ror:8 row_mask:0xf bank_mask:0xf
	v_mov_b32_dpp v227, v141 row_ror:8 row_mask:0xf bank_mask:0xf
	v_mov_b32_dpp v228, v142 row_ror:8 row_mask:0xf bank_mask:0xf
	v_mov_b32_dpp v229, v143 row_ror:8 row_mask:0xf bank_mask:0xf
	v_cndmask_b32_e32 v230, v140, v136, vcc
	v_cndmask_b32_e32 v231, v141, v137, vcc
	v_cndmask_b32_e32 v232, v142, v138, vcc
	v_cndmask_b32_e32 v233, v143, v139, vcc
	v_cndmask_b32_e32 v222, v226, v222, vcc
	v_cndmask_b32_e32 v223, v227, v223, vcc
	v_cndmask_b32_e32 v224, v228, v224, vcc
	v_cndmask_b32_e32 v225, v229, v225, vcc
	v_pk_add_f32 v[116:117], v[230:231], v[116:117]
	v_pk_add_f32 v[118:119], v[232:233], v[118:119]
	v_pk_add_f32 v[108:109], v[222:223], v[108:109]
	v_pk_add_f32 v[110:111], v[224:225], v[110:111]
	v_add_u32_e32 v236, v163, v234
	v_add_u32_e32 v237, v163, v235
	global_load_dwordx4 v[128:131], v236, s[14:15]
	global_load_dwordx4 v[132:135], v237, s[14:15]
	global_load_dwordx4 v[136:139], v236, s[14:15] offset:512
	global_load_dwordx4 v[140:143], v237, s[14:15] offset:512
	v_add_u32_e32 v236, v160, v234
	v_add_u32_e32 v237, v160, v235
	v_mov_b32_dpp v222, v120 row_ror:8 row_mask:0xf bank_mask:0xf
	v_mov_b32_dpp v223, v121 row_ror:8 row_mask:0xf bank_mask:0xf
	v_mov_b32_dpp v224, v122 row_ror:8 row_mask:0xf bank_mask:0xf
	v_mov_b32_dpp v225, v123 row_ror:8 row_mask:0xf bank_mask:0xf
	v_cndmask_b32_e32 v226, v222, v124, vcc
	v_cndmask_b32_e32 v227, v223, v125, vcc
	v_cndmask_b32_e32 v228, v224, v126, vcc
	v_cndmask_b32_e32 v229, v225, v127, vcc
	v_cndmask_b32_e32 v230, v124, v222, vcc
	v_cndmask_b32_e32 v231, v125, v223, vcc
	v_cndmask_b32_e32 v232, v126, v224, vcc
	v_cndmask_b32_e32 v233, v127, v225, vcc
	global_store_dwordx4 v236, v[226:229], s[72:73] sc1
	global_store_dwordx4 v237, v[230:233], s[72:73] sc1
	v_mov_b32_dpp v222, v108 row_ror:8 row_mask:0xf bank_mask:0xf
	v_mov_b32_dpp v223, v109 row_ror:8 row_mask:0xf bank_mask:0xf
	v_mov_b32_dpp v224, v110 row_ror:8 row_mask:0xf bank_mask:0xf
	v_mov_b32_dpp v225, v111 row_ror:8 row_mask:0xf bank_mask:0xf
	v_cndmask_b32_e32 v226, v222, v116, vcc
	v_cndmask_b32_e32 v227, v223, v117, vcc
	v_cndmask_b32_e32 v228, v224, v118, vcc
	v_cndmask_b32_e32 v229, v225, v119, vcc
	v_cndmask_b32_e32 v230, v116, v222, vcc
	v_cndmask_b32_e32 v231, v117, v223, vcc
	v_cndmask_b32_e32 v232, v118, v224, vcc
	v_cndmask_b32_e32 v233, v119, v225, vcc
	global_store_dwordx4 v236, v[226:229], s[72:73] offset:512 sc1
	global_store_dwordx4 v237, v[230:233], s[72:73] offset:512 sc1
	v_lshrrev_b32_e32 v236, 1, v160
	v_add_u32_e32 v236, v236, v245
	v_cvt_pk_bf16_f32 v194, v124, v125
	v_cvt_pk_bf16_f32 v195, v126, v127
	v_mul_f32_e32 v246, v125, v125
	v_mul_f32_e32 v247, v127, v127
	v_fmac_f32_e32 v246, v124, v124
	v_fmac_f32_e32 v247, v126, v126
	v_add_f32_e32 v180, v246, v247
	v_cvt_pk_bf16_f32 v196, v120, v121
	v_cvt_pk_bf16_f32 v197, v122, v123
	v_mul_f32_e32 v246, v121, v121
	v_mul_f32_e32 v247, v123, v123
	v_fmac_f32_e32 v246, v120, v120
	v_fmac_f32_e32 v247, v122, v122
	v_add_f32_e32 v246, v246, v247
	v_add_f32_e32 v180, v246, v180
	v_permlane16_swap_b32_e32 v194, v196
	v_permlane16_swap_b32_e32 v195, v197
	global_store_dwordx4 v236, v[194:197], s[22:23] sc1
	s_nop 1
	v_cvt_pk_bf16_f32 v194, v116, v117
	v_cvt_pk_bf16_f32 v195, v118, v119
	v_mul_f32_e32 v246, v117, v117
	v_mul_f32_e32 v247, v119, v119
	v_fmac_f32_e32 v246, v116, v116
	v_fmac_f32_e32 v247, v118, v118
	v_add_f32_e32 v246, v246, v247
	v_add_f32_e32 v180, v246, v180
	v_cvt_pk_bf16_f32 v196, v108, v109
	v_cvt_pk_bf16_f32 v197, v110, v111
	v_mul_f32_e32 v246, v109, v109
	v_mul_f32_e32 v247, v111, v111
	v_fmac_f32_e32 v246, v108, v108
	v_fmac_f32_e32 v247, v110, v110
	v_add_f32_e32 v246, v246, v247
	v_add_f32_e32 v180, v246, v180
	v_permlane16_swap_b32_e32 v194, v196
	v_permlane16_swap_b32_e32 v195, v197
	global_store_dwordx4 v236, v[194:197], s[22:23] offset:256 sc1
	s_nop 1
	s_waitcnt vmcnt(14)
; __device__ __forceinline__ unsigned cvt_pk_bf16(float lo, float hi) { unsigned r; asm volatile("v_cvt_pk_bf16_f32 %0, %1, %2" : "=v"(r) : "v"(lo), "v"(hi)); return r; }
;     __device__ __forceinline__ void operator()(const f32x4 (&acc)[2][2][4][2], const Unit& u, int wr, int wc, int fr, int fq) const {
;     ...
; #pragma unroll
;         for (int gi = 0; gi < 8; ++gi) {
;             const int ai = gi >> 2, m = gi & 3;
;             const int row = row0 + ai * HALF + m * 16;
;             const size_t off = (size_t)row * ldc + col0;
;             if (gi + 1 < 8) {
;                 const size_t offn = (size_t)(row0 + ((gi + 1) >> 2) * HALF + ((gi + 1) & 3) * 16) * ldc + col0;
; #pragma unroll
;                 for (int q = 0; q < 4; ++q) bs[(gi + 1) & 1][q] = *(const f32x4*)(xin + offn + (q >> 1) * HALF + (q & 1) * 16);
;             }
;             float sq = 0.f;
; #pragma unroll
;             for (int q = 0; q < 4; ++q) {
;                 const int bj = q >> 1, n = q & 1;
;                 const f32x4 o = bs[gi & 1][q] + acc[ai][bj][m][n];
;                 *(f32x4*)(out + off + bj * HALF + n * 16) = o;
;                 if (ss) {
;                     u32x2 w; w.x = cvt_pk_bf16(o[0], o[1]); w.y = cvt_pk_bf16(o[2], o[3]);
;                     *(u32x2*)(xb + off + bj * HALF + n * 16) = w;
;                     sq += (o[0] * o[0] + o[1] * o[1]) + (o[2] * o[2] + o[3] * o[3]);
;                 }
;             }
	v_mov_b32_dpp v222, v144 row_ror:8 row_mask:0xf bank_mask:0xf
	v_mov_b32_dpp v223, v145 row_ror:8 row_mask:0xf bank_mask:0xf
	v_mov_b32_dpp v224, v146 row_ror:8 row_mask:0xf bank_mask:0xf
	v_mov_b32_dpp v225, v147 row_ror:8 row_mask:0xf bank_mask:0xf
	v_mov_b32_dpp v226, v148 row_ror:8 row_mask:0xf bank_mask:0xf
	v_mov_b32_dpp v227, v149 row_ror:8 row_mask:0xf bank_mask:0xf
	v_mov_b32_dpp v228, v150 row_ror:8 row_mask:0xf bank_mask:0xf
	v_mov_b32_dpp v229, v151 row_ror:8 row_mask:0xf bank_mask:0xf
	v_cndmask_b32_e32 v230, v148, v144, vcc
	v_cndmask_b32_e32 v231, v149, v145, vcc
	v_cndmask_b32_e32 v232, v150, v146, vcc
	v_cndmask_b32_e32 v233, v151, v147, vcc
	v_cndmask_b32_e32 v222, v226, v222, vcc
	v_cndmask_b32_e32 v223, v227, v223, vcc
	v_cndmask_b32_e32 v224, v228, v224, vcc
	v_cndmask_b32_e32 v225, v229, v225, vcc
	v_pk_add_f32 v[112:113], v[230:231], v[112:113]
	v_pk_add_f32 v[114:115], v[232:233], v[114:115]
	v_pk_add_f32 v[104:105], v[222:223], v[104:105]
	v_pk_add_f32 v[106:107], v[224:225], v[106:107]
	v_mov_b32_dpp v222, v152 row_ror:8 row_mask:0xf bank_mask:0xf
	v_mov_b32_dpp v223, v153 row_ror:8 row_mask:0xf bank_mask:0xf
	v_mov_b32_dpp v224, v154 row_ror:8 row_mask:0xf bank_mask:0xf
	v_mov_b32_dpp v225, v155 row_ror:8 row_mask:0xf bank_mask:0xf
	v_mov_b32_dpp v226, v156 row_ror:8 row_mask:0xf bank_mask:0xf
	v_mov_b32_dpp v227, v157 row_ror:8 row_mask:0xf bank_mask:0xf
	v_mov_b32_dpp v228, v158 row_ror:8 row_mask:0xf bank_mask:0xf
	v_mov_b32_dpp v229, v159 row_ror:8 row_mask:0xf bank_mask:0xf
	v_cndmask_b32_e32 v230, v156, v152, vcc
	v_cndmask_b32_e32 v231, v157, v153, vcc
	v_cndmask_b32_e32 v232, v158, v154, vcc
	v_cndmask_b32_e32 v233, v159, v155, vcc
	v_cndmask_b32_e32 v222, v226, v222, vcc
	v_cndmask_b32_e32 v223, v227, v223, vcc
	v_cndmask_b32_e32 v224, v228, v224, vcc
	v_cndmask_b32_e32 v225, v229, v225, vcc
	v_pk_add_f32 v[100:101], v[230:231], v[100:101]
	v_pk_add_f32 v[102:103], v[232:233], v[102:103]
	v_pk_add_f32 v[92:93], v[222:223], v[92:93]
	v_pk_add_f32 v[94:95], v[224:225], v[94:95]
	v_add_u32_e32 v236, v164, v234
	v_add_u32_e32 v237, v164, v235
	global_load_dwordx4 v[144:147], v236, s[14:15]
	global_load_dwordx4 v[148:151], v237, s[14:15]
	global_load_dwordx4 v[152:155], v236, s[14:15] offset:512
	global_load_dwordx4 v[156:159], v237, s[14:15] offset:512
	v_add_u32_e32 v236, v161, v234
	v_add_u32_e32 v237, v161, v235
	v_mov_b32_dpp v222, v104 row_ror:8 row_mask:0xf bank_mask:0xf
	v_mov_b32_dpp v223, v105 row_ror:8 row_mask:0xf bank_mask:0xf
	v_mov_b32_dpp v224, v106 row_ror:8 row_mask:0xf bank_mask:0xf
	v_mov_b32_dpp v225, v107 row_ror:8 row_mask:0xf bank_mask:0xf
	v_cndmask_b32_e32 v226, v222, v112, vcc
	v_cndmask_b32_e32 v227, v223, v113, vcc
	v_cndmask_b32_e32 v228, v224, v114, vcc
	v_cndmask_b32_e32 v229, v225, v115, vcc
	v_cndmask_b32_e32 v230, v112, v222, vcc
	v_cndmask_b32_e32 v231, v113, v223, vcc
	v_cndmask_b32_e32 v232, v114, v224, vcc
	v_cndmask_b32_e32 v233, v115, v225, vcc
	global_store_dwordx4 v236, v[226:229], s[72:73] sc1
	global_store_dwordx4 v237, v[230:233], s[72:73] sc1
	v_mov_b32_dpp v222, v92 row_ror:8 row_mask:0xf bank_mask:0xf
	v_mov_b32_dpp v223, v93 row_ror:8 row_mask:0xf bank_mask:0xf
	v_mov_b32_dpp v224, v94 row_ror:8 row_mask:0xf bank_mask:0xf
	v_mov_b32_dpp v225, v95 row_ror:8 row_mask:0xf bank_mask:0xf
	v_cndmask_b32_e32 v226, v222, v100, vcc
	v_cndmask_b32_e32 v227, v223, v101, vcc
	v_cndmask_b32_e32 v228, v224, v102, vcc
	v_cndmask_b32_e32 v229, v225, v103, vcc
	v_cndmask_b32_e32 v230, v100, v222, vcc
	v_cndmask_b32_e32 v231, v101, v223, vcc
	v_cndmask_b32_e32 v232, v102, v224, vcc
	v_cndmask_b32_e32 v233, v103, v225, vcc
	global_store_dwordx4 v236, v[226:229], s[72:73] offset:512 sc1
	global_store_dwordx4 v237, v[230:233], s[72:73] offset:512 sc1
	v_lshrrev_b32_e32 v236, 1, v161
	v_add_u32_e32 v236, v236, v245
	v_cvt_pk_bf16_f32 v194, v112, v113
	v_cvt_pk_bf16_f32 v195, v114, v115
	v_mul_f32_e32 v246, v113, v113
	v_mul_f32_e32 v247, v115, v115
	v_fmac_f32_e32 v246, v112, v112
	v_fmac_f32_e32 v247, v114, v114
	v_add_f32_e32 v181, v246, v247
	v_cvt_pk_bf16_f32 v196, v104, v105
	v_cvt_pk_bf16_f32 v197, v106, v107
	v_mul_f32_e32 v246, v105, v105
	v_mul_f32_e32 v247, v107, v107
	v_fmac_f32_e32 v246, v104, v104
	v_fmac_f32_e32 v247, v106, v106
	v_add_f32_e32 v246, v246, v247
	v_add_f32_e32 v181, v246, v181
	v_permlane16_swap_b32_e32 v194, v196
	v_permlane16_swap_b32_e32 v195, v197
	global_store_dwordx4 v236, v[194:197], s[22:23] sc1
	s_nop 1
	v_cvt_pk_bf16_f32 v194, v100, v101
	v_cvt_pk_bf16_f32 v195, v102, v103
	v_mul_f32_e32 v246, v101, v101
	v_mul_f32_e32 v247, v103, v103
	v_fmac_f32_e32 v246, v100, v100
	v_fmac_f32_e32 v247, v102, v102
	v_add_f32_e32 v246, v246, v247
	v_add_f32_e32 v181, v246, v181
	v_cvt_pk_bf16_f32 v196, v92, v93
	v_cvt_pk_bf16_f32 v197, v94, v95
	v_mul_f32_e32 v246, v93, v93
	v_mul_f32_e32 v247, v95, v95
	v_fmac_f32_e32 v246, v92, v92
	v_fmac_f32_e32 v247, v94, v94
	v_add_f32_e32 v246, v246, v247
	v_add_f32_e32 v181, v246, v181
	v_permlane16_swap_b32_e32 v194, v196
	v_permlane16_swap_b32_e32 v195, v197
	global_store_dwordx4 v236, v[194:197], s[22:23] offset:256 sc1
	s_nop 1
	s_waitcnt vmcnt(20)
; __device__ __forceinline__ unsigned cvt_pk_bf16(float lo, float hi) { unsigned r; asm volatile("v_cvt_pk_bf16_f32 %0, %1, %2" : "=v"(r) : "v"(lo), "v"(hi)); return r; }
;     __device__ __forceinline__ void operator()(const f32x4 (&acc)[2][2][4][2], const Unit& u, int wr, int wc, int fr, int fq) const {
;     ...
; #pragma unroll
;         for (int gi = 0; gi < 8; ++gi) {
;             const int ai = gi >> 2, m = gi & 3;
;             const int row = row0 + ai * HALF + m * 16;
;             const size_t off = (size_t)row * ldc + col0;
;             if (gi + 1 < 8) {
;                 const size_t offn = (size_t)(row0 + ((gi + 1) >> 2) * HALF + ((gi + 1) & 3) * 16) * ldc + col0;
; #pragma unroll
;                 for (int q = 0; q < 4; ++q) bs[(gi + 1) & 1][q] = *(const f32x4*)(xin + offn + (q >> 1) * HALF + (q & 1) * 16);
;             }
;             float sq = 0.f;
; #pragma unroll
;             for (int q = 0; q < 4; ++q) {
;                 const int bj = q >> 1, n = q & 1;
;                 const f32x4 o = bs[gi & 1][q] + acc[ai][bj][m][n];
;                 *(f32x4*)(out + off + bj * HALF + n * 16) = o;
;                 if (ss) {
;                     u32x2 w; w.x = cvt_pk_bf16(o[0], o[1]); w.y = cvt_pk_bf16(o[2], o[3]);
;                     *(u32x2*)(xb + off + bj * HALF + n * 16) = w;
;                     sq += (o[0] * o[0] + o[1] * o[1]) + (o[2] * o[2] + o[3] * o[3]);
;                 }
;             }
	v_mov_b32_dpp v222, v206 row_ror:8 row_mask:0xf bank_mask:0xf
	v_mov_b32_dpp v223, v207 row_ror:8 row_mask:0xf bank_mask:0xf
	v_mov_b32_dpp v224, v208 row_ror:8 row_mask:0xf bank_mask:0xf
	v_mov_b32_dpp v225, v209 row_ror:8 row_mask:0xf bank_mask:0xf
	v_mov_b32_dpp v226, v210 row_ror:8 row_mask:0xf bank_mask:0xf
	v_mov_b32_dpp v227, v211 row_ror:8 row_mask:0xf bank_mask:0xf
	v_mov_b32_dpp v228, v212 row_ror:8 row_mask:0xf bank_mask:0xf
	v_mov_b32_dpp v229, v213 row_ror:8 row_mask:0xf bank_mask:0xf
	v_cndmask_b32_e32 v230, v210, v206, vcc
	v_cndmask_b32_e32 v231, v211, v207, vcc
	v_cndmask_b32_e32 v232, v212, v208, vcc
	v_cndmask_b32_e32 v233, v213, v209, vcc
	v_cndmask_b32_e32 v222, v226, v222, vcc
	v_cndmask_b32_e32 v223, v227, v223, vcc
	v_cndmask_b32_e32 v224, v228, v224, vcc
	v_cndmask_b32_e32 v225, v229, v225, vcc
	v_pk_add_f32 v[96:97], v[230:231], v[96:97]
	v_pk_add_f32 v[98:99], v[232:233], v[98:99]
	v_pk_add_f32 v[88:89], v[222:223], v[88:89]
	v_pk_add_f32 v[90:91], v[224:225], v[90:91]
	v_mov_b32_dpp v222, v214 row_ror:8 row_mask:0xf bank_mask:0xf
	v_mov_b32_dpp v223, v215 row_ror:8 row_mask:0xf bank_mask:0xf
	v_mov_b32_dpp v224, v216 row_ror:8 row_mask:0xf bank_mask:0xf
	v_mov_b32_dpp v225, v217 row_ror:8 row_mask:0xf bank_mask:0xf
	v_mov_b32_dpp v226, v218 row_ror:8 row_mask:0xf bank_mask:0xf
	v_mov_b32_dpp v227, v219 row_ror:8 row_mask:0xf bank_mask:0xf
	v_mov_b32_dpp v228, v220 row_ror:8 row_mask:0xf bank_mask:0xf
	v_mov_b32_dpp v229, v221 row_ror:8 row_mask:0xf bank_mask:0xf
	v_cndmask_b32_e32 v230, v218, v214, vcc
	v_cndmask_b32_e32 v231, v219, v215, vcc
	v_cndmask_b32_e32 v232, v220, v216, vcc
	v_cndmask_b32_e32 v233, v221, v217, vcc
	v_cndmask_b32_e32 v222, v226, v222, vcc
	v_cndmask_b32_e32 v223, v227, v223, vcc
	v_cndmask_b32_e32 v224, v228, v224, vcc
	v_cndmask_b32_e32 v225, v229, v225, vcc
	v_pk_add_f32 v[84:85], v[230:231], v[84:85]
	v_pk_add_f32 v[86:87], v[232:233], v[86:87]
	v_pk_add_f32 v[76:77], v[222:223], v[76:77]
	v_pk_add_f32 v[78:79], v[224:225], v[78:79]
	v_add_u32_e32 v236, v165, v234
	v_add_u32_e32 v237, v165, v235
	global_load_dwordx4 v[206:209], v236, s[14:15]
	global_load_dwordx4 v[210:213], v237, s[14:15]
	global_load_dwordx4 v[214:217], v236, s[14:15] offset:512
	global_load_dwordx4 v[218:221], v237, s[14:15] offset:512
	v_add_u32_e32 v236, v162, v234
	v_add_u32_e32 v237, v162, v235
	v_mov_b32_dpp v222, v88 row_ror:8 row_mask:0xf bank_mask:0xf
	v_mov_b32_dpp v223, v89 row_ror:8 row_mask:0xf bank_mask:0xf
	v_mov_b32_dpp v224, v90 row_ror:8 row_mask:0xf bank_mask:0xf
	v_mov_b32_dpp v225, v91 row_ror:8 row_mask:0xf bank_mask:0xf
	v_cndmask_b32_e32 v226, v222, v96, vcc
	v_cndmask_b32_e32 v227, v223, v97, vcc
	v_cndmask_b32_e32 v228, v224, v98, vcc
	v_cndmask_b32_e32 v229, v225, v99, vcc
	v_cndmask_b32_e32 v230, v96, v222, vcc
	v_cndmask_b32_e32 v231, v97, v223, vcc
	v_cndmask_b32_e32 v232, v98, v224, vcc
	v_cndmask_b32_e32 v233, v99, v225, vcc
	global_store_dwordx4 v236, v[226:229], s[72:73] sc1
	global_store_dwordx4 v237, v[230:233], s[72:73] sc1
	v_mov_b32_dpp v222, v76 row_ror:8 row_mask:0xf bank_mask:0xf
	v_mov_b32_dpp v223, v77 row_ror:8 row_mask:0xf bank_mask:0xf
	v_mov_b32_dpp v224, v78 row_ror:8 row_mask:0xf bank_mask:0xf
	v_mov_b32_dpp v225, v79 row_ror:8 row_mask:0xf bank_mask:0xf
	v_cndmask_b32_e32 v226, v222, v84, vcc
	v_cndmask_b32_e32 v227, v223, v85, vcc
	v_cndmask_b32_e32 v228, v224, v86, vcc
	v_cndmask_b32_e32 v229, v225, v87, vcc
	v_cndmask_b32_e32 v230, v84, v222, vcc
	v_cndmask_b32_e32 v231, v85, v223, vcc
	v_cndmask_b32_e32 v232, v86, v224, vcc
	v_cndmask_b32_e32 v233, v87, v225, vcc
	global_store_dwordx4 v236, v[226:229], s[72:73] offset:512 sc1
	global_store_dwordx4 v237, v[230:233], s[72:73] offset:512 sc1
	v_lshrrev_b32_e32 v236, 1, v162
	v_add_u32_e32 v236, v236, v245
	v_cvt_pk_bf16_f32 v194, v96, v97
	v_cvt_pk_bf16_f32 v195, v98, v99
	v_mul_f32_e32 v246, v97, v97
	v_mul_f32_e32 v247, v99, v99
	v_fmac_f32_e32 v246, v96, v96
	v_fmac_f32_e32 v247, v98, v98
	v_add_f32_e32 v182, v246, v247
	v_cvt_pk_bf16_f32 v196, v88, v89
	v_cvt_pk_bf16_f32 v197, v90, v91
	v_mul_f32_e32 v246, v89, v89
	v_mul_f32_e32 v247, v91, v91
	v_fmac_f32_e32 v246, v88, v88
	v_fmac_f32_e32 v247, v90, v90
	v_add_f32_e32 v246, v246, v247
	v_add_f32_e32 v182, v246, v182
	v_permlane16_swap_b32_e32 v194, v196
	v_permlane16_swap_b32_e32 v195, v197
	global_store_dwordx4 v236, v[194:197], s[22:23] sc1
	s_nop 1
	v_cvt_pk_bf16_f32 v194, v84, v85
	v_cvt_pk_bf16_f32 v195, v86, v87
	v_mul_f32_e32 v246, v85, v85
	v_mul_f32_e32 v247, v87, v87
	v_fmac_f32_e32 v246, v84, v84
	v_fmac_f32_e32 v247, v86, v86
	v_add_f32_e32 v246, v246, v247
	v_add_f32_e32 v182, v246, v182
	v_cvt_pk_bf16_f32 v196, v76, v77
	v_cvt_pk_bf16_f32 v197, v78, v79
	v_mul_f32_e32 v246, v77, v77
	v_mul_f32_e32 v247, v79, v79
	v_fmac_f32_e32 v246, v76, v76
	v_fmac_f32_e32 v247, v78, v78
	v_add_f32_e32 v246, v246, v247
	v_add_f32_e32 v182, v246, v182
	v_permlane16_swap_b32_e32 v194, v196
	v_permlane16_swap_b32_e32 v195, v197
	global_store_dwordx4 v236, v[194:197], s[22:23] offset:256 sc1
	s_nop 1
	s_waitcnt vmcnt(26)
; __device__ __forceinline__ unsigned cvt_pk_bf16(float lo, float hi) { unsigned r; asm volatile("v_cvt_pk_bf16_f32 %0, %1, %2" : "=v"(r) : "v"(lo), "v"(hi)); return r; }
;     __device__ __forceinline__ void operator()(const f32x4 (&acc)[2][2][4][2], const Unit& u, int wr, int wc, int fr, int fq) const {
;     ...
; #pragma unroll
;         for (int gi = 0; gi < 8; ++gi) {
;             const int ai = gi >> 2, m = gi & 3;
;             const int row = row0 + ai * HALF + m * 16;
;             const size_t off = (size_t)row * ldc + col0;
;             if (gi + 1 < 8) {
;                 const size_t offn = (size_t)(row0 + ((gi + 1) >> 2) * HALF + ((gi + 1) & 3) * 16) * ldc + col0;
; #pragma unroll
;                 for (int q = 0; q < 4; ++q) bs[(gi + 1) & 1][q] = *(const f32x4*)(xin + offn + (q >> 1) * HALF + (q & 1) * 16);
;             }
;             float sq = 0.f;
; #pragma unroll
;             for (int q = 0; q < 4; ++q) {
;                 const int bj = q >> 1, n = q & 1;
;                 const f32x4 o = bs[gi & 1][q] + acc[ai][bj][m][n];
;                 *(f32x4*)(out + off + bj * HALF + n * 16) = o;
;                 if (ss) {
;                     u32x2 w; w.x = cvt_pk_bf16(o[0], o[1]); w.y = cvt_pk_bf16(o[2], o[3]);
;                     *(u32x2*)(xb + off + bj * HALF + n * 16) = w;
;                     sq += (o[0] * o[0] + o[1] * o[1]) + (o[2] * o[2] + o[3] * o[3]);
;                 }
;             }
	v_mov_b32_dpp v222, v128 row_ror:8 row_mask:0xf bank_mask:0xf
	v_mov_b32_dpp v223, v129 row_ror:8 row_mask:0xf bank_mask:0xf
	v_mov_b32_dpp v224, v130 row_ror:8 row_mask:0xf bank_mask:0xf
	v_mov_b32_dpp v225, v131 row_ror:8 row_mask:0xf bank_mask:0xf
	v_mov_b32_dpp v226, v132 row_ror:8 row_mask:0xf bank_mask:0xf
	v_mov_b32_dpp v227, v133 row_ror:8 row_mask:0xf bank_mask:0xf
	v_mov_b32_dpp v228, v134 row_ror:8 row_mask:0xf bank_mask:0xf
	v_mov_b32_dpp v229, v135 row_ror:8 row_mask:0xf bank_mask:0xf
	v_cndmask_b32_e32 v230, v132, v128, vcc
	v_cndmask_b32_e32 v231, v133, v129, vcc
	v_cndmask_b32_e32 v232, v134, v130, vcc
	v_cndmask_b32_e32 v233, v135, v131, vcc
	v_cndmask_b32_e32 v222, v226, v222, vcc
	v_cndmask_b32_e32 v223, v227, v223, vcc
	v_cndmask_b32_e32 v224, v228, v224, vcc
	v_cndmask_b32_e32 v225, v229, v225, vcc
	v_pk_add_f32 v[80:81], v[230:231], v[80:81]
	v_pk_add_f32 v[82:83], v[232:233], v[82:83]
	v_pk_add_f32 v[72:73], v[222:223], v[72:73]
	v_pk_add_f32 v[74:75], v[224:225], v[74:75]
	v_mov_b32_dpp v222, v136 row_ror:8 row_mask:0xf bank_mask:0xf
	v_mov_b32_dpp v223, v137 row_ror:8 row_mask:0xf bank_mask:0xf
	v_mov_b32_dpp v224, v138 row_ror:8 row_mask:0xf bank_mask:0xf
	v_mov_b32_dpp v225, v139 row_ror:8 row_mask:0xf bank_mask:0xf
	v_mov_b32_dpp v226, v140 row_ror:8 row_mask:0xf bank_mask:0xf
	v_mov_b32_dpp v227, v141 row_ror:8 row_mask:0xf bank_mask:0xf
	v_mov_b32_dpp v228, v142 row_ror:8 row_mask:0xf bank_mask:0xf
	v_mov_b32_dpp v229, v143 row_ror:8 row_mask:0xf bank_mask:0xf
	v_cndmask_b32_e32 v230, v140, v136, vcc
	v_cndmask_b32_e32 v231, v141, v137, vcc
	v_cndmask_b32_e32 v232, v142, v138, vcc
	v_cndmask_b32_e32 v233, v143, v139, vcc
	v_cndmask_b32_e32 v222, v226, v222, vcc
	v_cndmask_b32_e32 v223, v227, v223, vcc
	v_cndmask_b32_e32 v224, v228, v224, vcc
	v_cndmask_b32_e32 v225, v229, v225, vcc
	v_pk_add_f32 v[68:69], v[230:231], v[68:69]
	v_pk_add_f32 v[70:71], v[232:233], v[70:71]
	v_pk_add_f32 v[64:65], v[222:223], v[64:65]
	v_pk_add_f32 v[66:67], v[224:225], v[66:67]
	v_add_u32_e32 v236, v192, v234
	v_add_u32_e32 v237, v192, v235
	global_load_dwordx4 v[128:131], v236, s[14:15]
	global_load_dwordx4 v[132:135], v237, s[14:15]
	global_load_dwordx4 v[136:139], v236, s[14:15] offset:512
	global_load_dwordx4 v[140:143], v237, s[14:15] offset:512
	v_add_u32_e32 v236, v163, v234
	v_add_u32_e32 v237, v163, v235
	v_mov_b32_dpp v222, v72 row_ror:8 row_mask:0xf bank_mask:0xf
	v_mov_b32_dpp v223, v73 row_ror:8 row_mask:0xf bank_mask:0xf
	v_mov_b32_dpp v224, v74 row_ror:8 row_mask:0xf bank_mask:0xf
	v_mov_b32_dpp v225, v75 row_ror:8 row_mask:0xf bank_mask:0xf
	v_cndmask_b32_e32 v226, v222, v80, vcc
	v_cndmask_b32_e32 v227, v223, v81, vcc
	v_cndmask_b32_e32 v228, v224, v82, vcc
	v_cndmask_b32_e32 v229, v225, v83, vcc
	v_cndmask_b32_e32 v230, v80, v222, vcc
	v_cndmask_b32_e32 v231, v81, v223, vcc
	v_cndmask_b32_e32 v232, v82, v224, vcc
	v_cndmask_b32_e32 v233, v83, v225, vcc
	global_store_dwordx4 v236, v[226:229], s[72:73] sc1
	global_store_dwordx4 v237, v[230:233], s[72:73] sc1
	v_mov_b32_dpp v222, v64 row_ror:8 row_mask:0xf bank_mask:0xf
	v_mov_b32_dpp v223, v65 row_ror:8 row_mask:0xf bank_mask:0xf
	v_mov_b32_dpp v224, v66 row_ror:8 row_mask:0xf bank_mask:0xf
	v_mov_b32_dpp v225, v67 row_ror:8 row_mask:0xf bank_mask:0xf
	v_cndmask_b32_e32 v226, v222, v68, vcc
	v_cndmask_b32_e32 v227, v223, v69, vcc
	v_cndmask_b32_e32 v228, v224, v70, vcc
	v_cndmask_b32_e32 v229, v225, v71, vcc
	v_cndmask_b32_e32 v230, v68, v222, vcc
	v_cndmask_b32_e32 v231, v69, v223, vcc
	v_cndmask_b32_e32 v232, v70, v224, vcc
	v_cndmask_b32_e32 v233, v71, v225, vcc
	global_store_dwordx4 v236, v[226:229], s[72:73] offset:512 sc1
	global_store_dwordx4 v237, v[230:233], s[72:73] offset:512 sc1
	v_lshrrev_b32_e32 v236, 1, v163
	v_add_u32_e32 v236, v236, v245
	v_cvt_pk_bf16_f32 v194, v80, v81
	v_cvt_pk_bf16_f32 v195, v82, v83
	v_mul_f32_e32 v246, v81, v81
	v_mul_f32_e32 v247, v83, v83
	v_fmac_f32_e32 v246, v80, v80
	v_fmac_f32_e32 v247, v82, v82
	v_add_f32_e32 v183, v246, v247
	v_cvt_pk_bf16_f32 v196, v72, v73
	v_cvt_pk_bf16_f32 v197, v74, v75
	v_mul_f32_e32 v246, v73, v73
	v_mul_f32_e32 v247, v75, v75
	v_fmac_f32_e32 v246, v72, v72
	v_fmac_f32_e32 v247, v74, v74
	v_add_f32_e32 v246, v246, v247
	v_add_f32_e32 v183, v246, v183
	v_permlane16_swap_b32_e32 v194, v196
	v_permlane16_swap_b32_e32 v195, v197
	global_store_dwordx4 v236, v[194:197], s[22:23] sc1
	s_nop 1
	v_cvt_pk_bf16_f32 v194, v68, v69
	v_cvt_pk_bf16_f32 v195, v70, v71
	v_mul_f32_e32 v246, v69, v69
	v_mul_f32_e32 v247, v71, v71
	v_fmac_f32_e32 v246, v68, v68
	v_fmac_f32_e32 v247, v70, v70
	v_add_f32_e32 v246, v246, v247
	v_add_f32_e32 v183, v246, v183
	v_cvt_pk_bf16_f32 v196, v64, v65
	v_cvt_pk_bf16_f32 v197, v66, v67
	v_mul_f32_e32 v246, v65, v65
	v_mul_f32_e32 v247, v67, v67
	v_fmac_f32_e32 v246, v64, v64
	v_fmac_f32_e32 v247, v66, v66
	v_add_f32_e32 v246, v246, v247
	v_add_f32_e32 v183, v246, v183
	v_permlane16_swap_b32_e32 v194, v196
	v_permlane16_swap_b32_e32 v195, v197
	global_store_dwordx4 v236, v[194:197], s[22:23] offset:256 sc1
	s_nop 1
	s_waitcnt vmcnt(26)
; __device__ __forceinline__ unsigned cvt_pk_bf16(float lo, float hi) { unsigned r; asm volatile("v_cvt_pk_bf16_f32 %0, %1, %2" : "=v"(r) : "v"(lo), "v"(hi)); return r; }
;     __device__ __forceinline__ void operator()(const f32x4 (&acc)[2][2][4][2], const Unit& u, int wr, int wc, int fr, int fq) const {
;     ...
; #pragma unroll
;         for (int gi = 0; gi < 8; ++gi) {
;             const int ai = gi >> 2, m = gi & 3;
;             const int row = row0 + ai * HALF + m * 16;
;             const size_t off = (size_t)row * ldc + col0;
;             if (gi + 1 < 8) {
;                 const size_t offn = (size_t)(row0 + ((gi + 1) >> 2) * HALF + ((gi + 1) & 3) * 16) * ldc + col0;
; #pragma unroll
;                 for (int q = 0; q < 4; ++q) bs[(gi + 1) & 1][q] = *(const f32x4*)(xin + offn + (q >> 1) * HALF + (q & 1) * 16);
;             }
;             float sq = 0.f;
; #pragma unroll
;             for (int q = 0; q < 4; ++q) {
;                 const int bj = q >> 1, n = q & 1;
;                 const f32x4 o = bs[gi & 1][q] + acc[ai][bj][m][n];
;                 *(f32x4*)(out + off + bj * HALF + n * 16) = o;
;                 if (ss) {
;                     u32x2 w; w.x = cvt_pk_bf16(o[0], o[1]); w.y = cvt_pk_bf16(o[2], o[3]);
;                     *(u32x2*)(xb + off + bj * HALF + n * 16) = w;
;                     sq += (o[0] * o[0] + o[1] * o[1]) + (o[2] * o[2] + o[3] * o[3]);
;                 }
;             }
	v_mov_b32_dpp v222, v144 row_ror:8 row_mask:0xf bank_mask:0xf
	v_mov_b32_dpp v223, v145 row_ror:8 row_mask:0xf bank_mask:0xf
	v_mov_b32_dpp v224, v146 row_ror:8 row_mask:0xf bank_mask:0xf
	v_mov_b32_dpp v225, v147 row_ror:8 row_mask:0xf bank_mask:0xf
	v_mov_b32_dpp v226, v148 row_ror:8 row_mask:0xf bank_mask:0xf
	v_mov_b32_dpp v227, v149 row_ror:8 row_mask:0xf bank_mask:0xf
	v_mov_b32_dpp v228, v150 row_ror:8 row_mask:0xf bank_mask:0xf
	v_mov_b32_dpp v229, v151 row_ror:8 row_mask:0xf bank_mask:0xf
	v_cndmask_b32_e32 v230, v148, v144, vcc
	v_cndmask_b32_e32 v231, v149, v145, vcc
	v_cndmask_b32_e32 v232, v150, v146, vcc
	v_cndmask_b32_e32 v233, v151, v147, vcc
	v_cndmask_b32_e32 v222, v226, v222, vcc
	v_cndmask_b32_e32 v223, v227, v223, vcc
	v_cndmask_b32_e32 v224, v228, v224, vcc
	v_cndmask_b32_e32 v225, v229, v225, vcc
	v_pk_add_f32 v[60:61], v[230:231], v[60:61]
	v_pk_add_f32 v[62:63], v[232:233], v[62:63]
	v_pk_add_f32 v[56:57], v[222:223], v[56:57]
	v_pk_add_f32 v[58:59], v[224:225], v[58:59]
	v_mov_b32_dpp v222, v152 row_ror:8 row_mask:0xf bank_mask:0xf
	v_mov_b32_dpp v223, v153 row_ror:8 row_mask:0xf bank_mask:0xf
	v_mov_b32_dpp v224, v154 row_ror:8 row_mask:0xf bank_mask:0xf
	v_mov_b32_dpp v225, v155 row_ror:8 row_mask:0xf bank_mask:0xf
	v_mov_b32_dpp v226, v156 row_ror:8 row_mask:0xf bank_mask:0xf
	v_mov_b32_dpp v227, v157 row_ror:8 row_mask:0xf bank_mask:0xf
	v_mov_b32_dpp v228, v158 row_ror:8 row_mask:0xf bank_mask:0xf
	v_mov_b32_dpp v229, v159 row_ror:8 row_mask:0xf bank_mask:0xf
	v_cndmask_b32_e32 v230, v156, v152, vcc
	v_cndmask_b32_e32 v231, v157, v153, vcc
	v_cndmask_b32_e32 v232, v158, v154, vcc
	v_cndmask_b32_e32 v233, v159, v155, vcc
	v_cndmask_b32_e32 v222, v226, v222, vcc
	v_cndmask_b32_e32 v223, v227, v223, vcc
	v_cndmask_b32_e32 v224, v228, v224, vcc
	v_cndmask_b32_e32 v225, v229, v225, vcc
	v_pk_add_f32 v[52:53], v[230:231], v[52:53]
	v_pk_add_f32 v[54:55], v[232:233], v[54:55]
	v_pk_add_f32 v[44:45], v[222:223], v[44:45]
	v_pk_add_f32 v[46:47], v[224:225], v[46:47]
	v_add_u32_e32 v236, v193, v234
	v_add_u32_e32 v237, v193, v235
	global_load_dwordx4 v[144:147], v236, s[14:15]
	global_load_dwordx4 v[148:151], v237, s[14:15]
	global_load_dwordx4 v[152:155], v236, s[14:15] offset:512
	global_load_dwordx4 v[156:159], v237, s[14:15] offset:512
	v_add_u32_e32 v236, v164, v234
	v_add_u32_e32 v237, v164, v235
	v_mov_b32_dpp v222, v56 row_ror:8 row_mask:0xf bank_mask:0xf
	v_mov_b32_dpp v223, v57 row_ror:8 row_mask:0xf bank_mask:0xf
	v_mov_b32_dpp v224, v58 row_ror:8 row_mask:0xf bank_mask:0xf
	v_mov_b32_dpp v225, v59 row_ror:8 row_mask:0xf bank_mask:0xf
	v_cndmask_b32_e32 v226, v222, v60, vcc
	v_cndmask_b32_e32 v227, v223, v61, vcc
	v_cndmask_b32_e32 v228, v224, v62, vcc
	v_cndmask_b32_e32 v229, v225, v63, vcc
	v_cndmask_b32_e32 v230, v60, v222, vcc
	v_cndmask_b32_e32 v231, v61, v223, vcc
	v_cndmask_b32_e32 v232, v62, v224, vcc
	v_cndmask_b32_e32 v233, v63, v225, vcc
	global_store_dwordx4 v236, v[226:229], s[72:73] sc1
	global_store_dwordx4 v237, v[230:233], s[72:73] sc1
	v_mov_b32_dpp v222, v44 row_ror:8 row_mask:0xf bank_mask:0xf
	v_mov_b32_dpp v223, v45 row_ror:8 row_mask:0xf bank_mask:0xf
	v_mov_b32_dpp v224, v46 row_ror:8 row_mask:0xf bank_mask:0xf
	v_mov_b32_dpp v225, v47 row_ror:8 row_mask:0xf bank_mask:0xf
	v_cndmask_b32_e32 v226, v222, v52, vcc
	v_cndmask_b32_e32 v227, v223, v53, vcc
	v_cndmask_b32_e32 v228, v224, v54, vcc
	v_cndmask_b32_e32 v229, v225, v55, vcc
	v_cndmask_b32_e32 v230, v52, v222, vcc
	v_cndmask_b32_e32 v231, v53, v223, vcc
	v_cndmask_b32_e32 v232, v54, v224, vcc
	v_cndmask_b32_e32 v233, v55, v225, vcc
	global_store_dwordx4 v236, v[226:229], s[72:73] offset:512 sc1
	global_store_dwordx4 v237, v[230:233], s[72:73] offset:512 sc1
	v_lshrrev_b32_e32 v236, 1, v164
	v_add_u32_e32 v236, v236, v245
	v_cvt_pk_bf16_f32 v194, v60, v61
	v_cvt_pk_bf16_f32 v195, v62, v63
	v_mul_f32_e32 v246, v61, v61
	v_mul_f32_e32 v247, v63, v63
	v_fmac_f32_e32 v246, v60, v60
	v_fmac_f32_e32 v247, v62, v62
	v_add_f32_e32 v184, v246, v247
	v_cvt_pk_bf16_f32 v196, v56, v57
	v_cvt_pk_bf16_f32 v197, v58, v59
	v_mul_f32_e32 v246, v57, v57
	v_mul_f32_e32 v247, v59, v59
	v_fmac_f32_e32 v246, v56, v56
	v_fmac_f32_e32 v247, v58, v58
	v_add_f32_e32 v246, v246, v247
	v_add_f32_e32 v184, v246, v184
	v_permlane16_swap_b32_e32 v194, v196
	v_permlane16_swap_b32_e32 v195, v197
	global_store_dwordx4 v236, v[194:197], s[22:23] sc1
	s_nop 1
	v_cvt_pk_bf16_f32 v194, v52, v53
	v_cvt_pk_bf16_f32 v195, v54, v55
	v_mul_f32_e32 v246, v53, v53
	v_mul_f32_e32 v247, v55, v55
	v_fmac_f32_e32 v246, v52, v52
	v_fmac_f32_e32 v247, v54, v54
	v_add_f32_e32 v246, v246, v247
	v_add_f32_e32 v184, v246, v184
	v_cvt_pk_bf16_f32 v196, v44, v45
	v_cvt_pk_bf16_f32 v197, v46, v47
	v_mul_f32_e32 v246, v45, v45
	v_mul_f32_e32 v247, v47, v47
	v_fmac_f32_e32 v246, v44, v44
	v_fmac_f32_e32 v247, v46, v46
	v_add_f32_e32 v246, v246, v247
	v_add_f32_e32 v184, v246, v184
	v_permlane16_swap_b32_e32 v194, v196
	v_permlane16_swap_b32_e32 v195, v197
	global_store_dwordx4 v236, v[194:197], s[22:23] offset:256 sc1
	s_nop 1
	s_waitcnt vmcnt(26)
; __device__ __forceinline__ unsigned cvt_pk_bf16(float lo, float hi) { unsigned r; asm volatile("v_cvt_pk_bf16_f32 %0, %1, %2" : "=v"(r) : "v"(lo), "v"(hi)); return r; }
;     __device__ __forceinline__ void operator()(const f32x4 (&acc)[2][2][4][2], const Unit& u, int wr, int wc, int fr, int fq) const {
;     ...
; #pragma unroll
;         for (int gi = 0; gi < 8; ++gi) {
;             const int ai = gi >> 2, m = gi & 3;
;             const int row = row0 + ai * HALF + m * 16;
;             const size_t off = (size_t)row * ldc + col0;
;             if (gi + 1 < 8) {
;                 const size_t offn = (size_t)(row0 + ((gi + 1) >> 2) * HALF + ((gi + 1) & 3) * 16) * ldc + col0;
; #pragma unroll
;                 for (int q = 0; q < 4; ++q) bs[(gi + 1) & 1][q] = *(const f32x4*)(xin + offn + (q >> 1) * HALF + (q & 1) * 16);
;             }
;             float sq = 0.f;
; #pragma unroll
;             for (int q = 0; q < 4; ++q) {
;                 const int bj = q >> 1, n = q & 1;
;                 const f32x4 o = bs[gi & 1][q] + acc[ai][bj][m][n];
;                 *(f32x4*)(out + off + bj * HALF + n * 16) = o;
;                 if (ss) {
;                     u32x2 w; w.x = cvt_pk_bf16(o[0], o[1]); w.y = cvt_pk_bf16(o[2], o[3]);
;                     *(u32x2*)(xb + off + bj * HALF + n * 16) = w;
;                     sq += (o[0] * o[0] + o[1] * o[1]) + (o[2] * o[2] + o[3] * o[3]);
;                 }
;             }
	v_mov_b32_dpp v222, v206 row_ror:8 row_mask:0xf bank_mask:0xf
	v_mov_b32_dpp v223, v207 row_ror:8 row_mask:0xf bank_mask:0xf
	v_mov_b32_dpp v224, v208 row_ror:8 row_mask:0xf bank_mask:0xf
	v_mov_b32_dpp v225, v209 row_ror:8 row_mask:0xf bank_mask:0xf
	v_mov_b32_dpp v226, v210 row_ror:8 row_mask:0xf bank_mask:0xf
	v_mov_b32_dpp v227, v211 row_ror:8 row_mask:0xf bank_mask:0xf
	v_mov_b32_dpp v228, v212 row_ror:8 row_mask:0xf bank_mask:0xf
	v_mov_b32_dpp v229, v213 row_ror:8 row_mask:0xf bank_mask:0xf
	v_cndmask_b32_e32 v230, v210, v206, vcc
	v_cndmask_b32_e32 v231, v211, v207, vcc
	v_cndmask_b32_e32 v232, v212, v208, vcc
	v_cndmask_b32_e32 v233, v213, v209, vcc
	v_cndmask_b32_e32 v222, v226, v222, vcc
	v_cndmask_b32_e32 v223, v227, v223, vcc
	v_cndmask_b32_e32 v224, v228, v224, vcc
	v_cndmask_b32_e32 v225, v229, v225, vcc
	v_pk_add_f32 v[48:49], v[230:231], v[48:49]
	v_pk_add_f32 v[50:51], v[232:233], v[50:51]
	v_pk_add_f32 v[40:41], v[222:223], v[40:41]
	v_pk_add_f32 v[42:43], v[224:225], v[42:43]
	v_mov_b32_dpp v222, v214 row_ror:8 row_mask:0xf bank_mask:0xf
	v_mov_b32_dpp v223, v215 row_ror:8 row_mask:0xf bank_mask:0xf
	v_mov_b32_dpp v224, v216 row_ror:8 row_mask:0xf bank_mask:0xf
	v_mov_b32_dpp v225, v217 row_ror:8 row_mask:0xf bank_mask:0xf
	v_mov_b32_dpp v226, v218 row_ror:8 row_mask:0xf bank_mask:0xf
	v_mov_b32_dpp v227, v219 row_ror:8 row_mask:0xf bank_mask:0xf
	v_mov_b32_dpp v228, v220 row_ror:8 row_mask:0xf bank_mask:0xf
	v_mov_b32_dpp v229, v221 row_ror:8 row_mask:0xf bank_mask:0xf
	v_cndmask_b32_e32 v230, v218, v214, vcc
	v_cndmask_b32_e32 v231, v219, v215, vcc
	v_cndmask_b32_e32 v232, v220, v216, vcc
	v_cndmask_b32_e32 v233, v221, v217, vcc
	v_cndmask_b32_e32 v222, v226, v222, vcc
	v_cndmask_b32_e32 v223, v227, v223, vcc
	v_cndmask_b32_e32 v224, v228, v224, vcc
	v_cndmask_b32_e32 v225, v229, v225, vcc
	v_pk_add_f32 v[36:37], v[230:231], v[36:37]
	v_pk_add_f32 v[38:39], v[232:233], v[38:39]
	v_pk_add_f32 v[28:29], v[222:223], v[28:29]
	v_pk_add_f32 v[30:31], v[224:225], v[30:31]
	v_add_u32_e32 v236, v165, v234
	v_add_u32_e32 v237, v165, v235
	v_mov_b32_dpp v222, v40 row_ror:8 row_mask:0xf bank_mask:0xf
	v_mov_b32_dpp v223, v41 row_ror:8 row_mask:0xf bank_mask:0xf
	v_mov_b32_dpp v224, v42 row_ror:8 row_mask:0xf bank_mask:0xf
	v_mov_b32_dpp v225, v43 row_ror:8 row_mask:0xf bank_mask:0xf
	v_cndmask_b32_e32 v226, v222, v48, vcc
	v_cndmask_b32_e32 v227, v223, v49, vcc
	v_cndmask_b32_e32 v228, v224, v50, vcc
	v_cndmask_b32_e32 v229, v225, v51, vcc
	v_cndmask_b32_e32 v230, v48, v222, vcc
	v_cndmask_b32_e32 v231, v49, v223, vcc
	v_cndmask_b32_e32 v232, v50, v224, vcc
	v_cndmask_b32_e32 v233, v51, v225, vcc
	global_store_dwordx4 v236, v[226:229], s[72:73] sc1
	global_store_dwordx4 v237, v[230:233], s[72:73] sc1
	v_mov_b32_dpp v222, v28 row_ror:8 row_mask:0xf bank_mask:0xf
	v_mov_b32_dpp v223, v29 row_ror:8 row_mask:0xf bank_mask:0xf
	v_mov_b32_dpp v224, v30 row_ror:8 row_mask:0xf bank_mask:0xf
	v_mov_b32_dpp v225, v31 row_ror:8 row_mask:0xf bank_mask:0xf
	v_cndmask_b32_e32 v226, v222, v36, vcc
	v_cndmask_b32_e32 v227, v223, v37, vcc
	v_cndmask_b32_e32 v228, v224, v38, vcc
	v_cndmask_b32_e32 v229, v225, v39, vcc
	v_cndmask_b32_e32 v230, v36, v222, vcc
	v_cndmask_b32_e32 v231, v37, v223, vcc
	v_cndmask_b32_e32 v232, v38, v224, vcc
	v_cndmask_b32_e32 v233, v39, v225, vcc
	global_store_dwordx4 v236, v[226:229], s[72:73] offset:512 sc1
	global_store_dwordx4 v237, v[230:233], s[72:73] offset:512 sc1
	v_lshrrev_b32_e32 v236, 1, v165
	v_add_u32_e32 v236, v236, v245
	v_cvt_pk_bf16_f32 v194, v48, v49
	v_cvt_pk_bf16_f32 v195, v50, v51
	v_mul_f32_e32 v246, v49, v49
	v_mul_f32_e32 v247, v51, v51
	v_fmac_f32_e32 v246, v48, v48
	v_fmac_f32_e32 v247, v50, v50
	v_add_f32_e32 v185, v246, v247
	v_cvt_pk_bf16_f32 v196, v40, v41
	v_cvt_pk_bf16_f32 v197, v42, v43
	v_mul_f32_e32 v246, v41, v41
	v_mul_f32_e32 v247, v43, v43
	v_fmac_f32_e32 v246, v40, v40
	v_fmac_f32_e32 v247, v42, v42
	v_add_f32_e32 v246, v246, v247
	v_add_f32_e32 v185, v246, v185
	v_permlane16_swap_b32_e32 v194, v196
	v_permlane16_swap_b32_e32 v195, v197
	global_store_dwordx4 v236, v[194:197], s[22:23] sc1
	s_nop 1
	v_cvt_pk_bf16_f32 v194, v36, v37
	v_cvt_pk_bf16_f32 v195, v38, v39
	v_mul_f32_e32 v246, v37, v37
	v_mul_f32_e32 v247, v39, v39
	v_fmac_f32_e32 v246, v36, v36
	v_fmac_f32_e32 v247, v38, v38
	v_add_f32_e32 v246, v246, v247
	v_add_f32_e32 v185, v246, v185
	v_cvt_pk_bf16_f32 v196, v28, v29
	v_cvt_pk_bf16_f32 v197, v30, v31
	v_mul_f32_e32 v246, v29, v29
	v_mul_f32_e32 v247, v31, v31
	v_fmac_f32_e32 v246, v28, v28
	v_fmac_f32_e32 v247, v30, v30
	v_add_f32_e32 v246, v246, v247
	v_add_f32_e32 v185, v246, v185
	v_permlane16_swap_b32_e32 v194, v196
	v_permlane16_swap_b32_e32 v195, v197
	global_store_dwordx4 v236, v[194:197], s[22:23] offset:256 sc1
	s_nop 1
	s_waitcnt vmcnt(22)
; __device__ __forceinline__ unsigned cvt_pk_bf16(float lo, float hi) { unsigned r; asm volatile("v_cvt_pk_bf16_f32 %0, %1, %2" : "=v"(r) : "v"(lo), "v"(hi)); return r; }
;     __device__ __forceinline__ void operator()(const f32x4 (&acc)[2][2][4][2], const Unit& u, int wr, int wc, int fr, int fq) const {
;     ...
; #pragma unroll
;         for (int gi = 0; gi < 8; ++gi) {
;             const int ai = gi >> 2, m = gi & 3;
;             const int row = row0 + ai * HALF + m * 16;
;             const size_t off = (size_t)row * ldc + col0;
;             if (gi + 1 < 8) {
;                 const size_t offn = (size_t)(row0 + ((gi + 1) >> 2) * HALF + ((gi + 1) & 3) * 16) * ldc + col0;
; #pragma unroll
;                 for (int q = 0; q < 4; ++q) bs[(gi + 1) & 1][q] = *(const f32x4*)(xin + offn + (q >> 1) * HALF + (q & 1) * 16);
;             }
;             float sq = 0.f;
; #pragma unroll
;             for (int q = 0; q < 4; ++q) {
;                 const int bj = q >> 1, n = q & 1;
;                 const f32x4 o = bs[gi & 1][q] + acc[ai][bj][m][n];
;                 *(f32x4*)(out + off + bj * HALF + n * 16) = o;
;                 if (ss) {
;                     u32x2 w; w.x = cvt_pk_bf16(o[0], o[1]); w.y = cvt_pk_bf16(o[2], o[3]);
;                     *(u32x2*)(xb + off + bj * HALF + n * 16) = w;
;                     sq += (o[0] * o[0] + o[1] * o[1]) + (o[2] * o[2] + o[3] * o[3]);
;                 }
;             }
	v_mov_b32_dpp v222, v128 row_ror:8 row_mask:0xf bank_mask:0xf
	v_mov_b32_dpp v223, v129 row_ror:8 row_mask:0xf bank_mask:0xf
	v_mov_b32_dpp v224, v130 row_ror:8 row_mask:0xf bank_mask:0xf
	v_mov_b32_dpp v225, v131 row_ror:8 row_mask:0xf bank_mask:0xf
	v_mov_b32_dpp v226, v132 row_ror:8 row_mask:0xf bank_mask:0xf
	v_mov_b32_dpp v227, v133 row_ror:8 row_mask:0xf bank_mask:0xf
	v_mov_b32_dpp v228, v134 row_ror:8 row_mask:0xf bank_mask:0xf
	v_mov_b32_dpp v229, v135 row_ror:8 row_mask:0xf bank_mask:0xf
	v_cndmask_b32_e32 v230, v132, v128, vcc
	v_cndmask_b32_e32 v231, v133, v129, vcc
	v_cndmask_b32_e32 v232, v134, v130, vcc
	v_cndmask_b32_e32 v233, v135, v131, vcc
	v_cndmask_b32_e32 v222, v226, v222, vcc
	v_cndmask_b32_e32 v223, v227, v223, vcc
	v_cndmask_b32_e32 v224, v228, v224, vcc
	v_cndmask_b32_e32 v225, v229, v225, vcc
	v_pk_add_f32 v[32:33], v[230:231], v[32:33]
	v_pk_add_f32 v[34:35], v[232:233], v[34:35]
	v_pk_add_f32 v[24:25], v[222:223], v[24:25]
	v_pk_add_f32 v[26:27], v[224:225], v[26:27]
	v_mov_b32_dpp v222, v136 row_ror:8 row_mask:0xf bank_mask:0xf
	v_mov_b32_dpp v223, v137 row_ror:8 row_mask:0xf bank_mask:0xf
	v_mov_b32_dpp v224, v138 row_ror:8 row_mask:0xf bank_mask:0xf
	v_mov_b32_dpp v225, v139 row_ror:8 row_mask:0xf bank_mask:0xf
	v_mov_b32_dpp v226, v140 row_ror:8 row_mask:0xf bank_mask:0xf
	v_mov_b32_dpp v227, v141 row_ror:8 row_mask:0xf bank_mask:0xf
	v_mov_b32_dpp v228, v142 row_ror:8 row_mask:0xf bank_mask:0xf
	v_mov_b32_dpp v229, v143 row_ror:8 row_mask:0xf bank_mask:0xf
	v_cndmask_b32_e32 v230, v140, v136, vcc
	v_cndmask_b32_e32 v231, v141, v137, vcc
	v_cndmask_b32_e32 v232, v142, v138, vcc
	v_cndmask_b32_e32 v233, v143, v139, vcc
	v_cndmask_b32_e32 v222, v226, v222, vcc
	v_cndmask_b32_e32 v223, v227, v223, vcc
	v_cndmask_b32_e32 v224, v228, v224, vcc
	v_cndmask_b32_e32 v225, v229, v225, vcc
	v_pk_add_f32 v[20:21], v[230:231], v[20:21]
	v_pk_add_f32 v[22:23], v[232:233], v[22:23]
	v_pk_add_f32 v[12:13], v[222:223], v[12:13]
	v_pk_add_f32 v[14:15], v[224:225], v[14:15]
	v_add_u32_e32 v236, v192, v234
	v_add_u32_e32 v237, v192, v235
	v_mov_b32_dpp v222, v24 row_ror:8 row_mask:0xf bank_mask:0xf
	v_mov_b32_dpp v223, v25 row_ror:8 row_mask:0xf bank_mask:0xf
	v_mov_b32_dpp v224, v26 row_ror:8 row_mask:0xf bank_mask:0xf
	v_mov_b32_dpp v225, v27 row_ror:8 row_mask:0xf bank_mask:0xf
	v_cndmask_b32_e32 v226, v222, v32, vcc
	v_cndmask_b32_e32 v227, v223, v33, vcc
	v_cndmask_b32_e32 v228, v224, v34, vcc
	v_cndmask_b32_e32 v229, v225, v35, vcc
	v_cndmask_b32_e32 v230, v32, v222, vcc
	v_cndmask_b32_e32 v231, v33, v223, vcc
	v_cndmask_b32_e32 v232, v34, v224, vcc
	v_cndmask_b32_e32 v233, v35, v225, vcc
	global_store_dwordx4 v236, v[226:229], s[72:73] sc1
	global_store_dwordx4 v237, v[230:233], s[72:73] sc1
	v_mov_b32_dpp v222, v12 row_ror:8 row_mask:0xf bank_mask:0xf
	v_mov_b32_dpp v223, v13 row_ror:8 row_mask:0xf bank_mask:0xf
	v_mov_b32_dpp v224, v14 row_ror:8 row_mask:0xf bank_mask:0xf
	v_mov_b32_dpp v225, v15 row_ror:8 row_mask:0xf bank_mask:0xf
	v_cndmask_b32_e32 v226, v222, v20, vcc
	v_cndmask_b32_e32 v227, v223, v21, vcc
	v_cndmask_b32_e32 v228, v224, v22, vcc
	v_cndmask_b32_e32 v229, v225, v23, vcc
	v_cndmask_b32_e32 v230, v20, v222, vcc
	v_cndmask_b32_e32 v231, v21, v223, vcc
	v_cndmask_b32_e32 v232, v22, v224, vcc
	v_cndmask_b32_e32 v233, v23, v225, vcc
	global_store_dwordx4 v236, v[226:229], s[72:73] offset:512 sc1
	global_store_dwordx4 v237, v[230:233], s[72:73] offset:512 sc1
	v_lshrrev_b32_e32 v236, 1, v192
	v_add_u32_e32 v236, v236, v245
	v_cvt_pk_bf16_f32 v194, v32, v33
	v_cvt_pk_bf16_f32 v195, v34, v35
	v_mul_f32_e32 v246, v33, v33
	v_mul_f32_e32 v247, v35, v35
	v_fmac_f32_e32 v246, v32, v32
	v_fmac_f32_e32 v247, v34, v34
	v_add_f32_e32 v186, v246, v247
	v_cvt_pk_bf16_f32 v196, v24, v25
	v_cvt_pk_bf16_f32 v197, v26, v27
	v_mul_f32_e32 v246, v25, v25
	v_mul_f32_e32 v247, v27, v27
	v_fmac_f32_e32 v246, v24, v24
	v_fmac_f32_e32 v247, v26, v26
	v_add_f32_e32 v246, v246, v247
	v_add_f32_e32 v186, v246, v186
	v_permlane16_swap_b32_e32 v194, v196
	v_permlane16_swap_b32_e32 v195, v197
	global_store_dwordx4 v236, v[194:197], s[22:23] sc1
	s_nop 1
	v_cvt_pk_bf16_f32 v194, v20, v21
	v_cvt_pk_bf16_f32 v195, v22, v23
	v_mul_f32_e32 v246, v21, v21
	v_mul_f32_e32 v247, v23, v23
	v_fmac_f32_e32 v246, v20, v20
	v_fmac_f32_e32 v247, v22, v22
	v_add_f32_e32 v246, v246, v247
	v_add_f32_e32 v186, v246, v186
	v_cvt_pk_bf16_f32 v196, v12, v13
	v_cvt_pk_bf16_f32 v197, v14, v15
	v_mul_f32_e32 v246, v13, v13
	v_mul_f32_e32 v247, v15, v15
	v_fmac_f32_e32 v246, v12, v12
	v_fmac_f32_e32 v247, v14, v14
	v_add_f32_e32 v246, v246, v247
	v_add_f32_e32 v186, v246, v186
	v_permlane16_swap_b32_e32 v194, v196
	v_permlane16_swap_b32_e32 v195, v197
	global_store_dwordx4 v236, v[194:197], s[22:23] offset:256 sc1
	s_nop 1
	s_waitcnt vmcnt(18)
; __device__ __forceinline__ unsigned cvt_pk_bf16(float lo, float hi) { unsigned r; asm volatile("v_cvt_pk_bf16_f32 %0, %1, %2" : "=v"(r) : "v"(lo), "v"(hi)); return r; }
;     __device__ __forceinline__ void operator()(const f32x4 (&acc)[2][2][4][2], const Unit& u, int wr, int wc, int fr, int fq) const {
;     ...
;             float sq = 0.f;
; #pragma unroll
;             for (int q = 0; q < 4; ++q) {
;                 const int bj = q >> 1, n = q & 1;
;                 const f32x4 o = bs[gi & 1][q] + acc[ai][bj][m][n];
;                 *(f32x4*)(out + off + bj * HALF + n * 16) = o;
;                 if (ss) {
;                     u32x2 w; w.x = cvt_pk_bf16(o[0], o[1]); w.y = cvt_pk_bf16(o[2], o[3]);
;                     *(u32x2*)(xb + off + bj * HALF + n * 16) = w;
;                     sq += (o[0] * o[0] + o[1] * o[1]) + (o[2] * o[2] + o[3] * o[3]);
;                 }
;             }
;             if (ss) { sq += __shfl_xor(sq, 16); sq += __shfl_xor(sq, 32); if (fq == 0) ss[(size_t)row * 32 + u.pn * 4 + wc] = sq; }
	v_mov_b32_dpp v222, v144 row_ror:8 row_mask:0xf bank_mask:0xf
	v_mov_b32_dpp v223, v145 row_ror:8 row_mask:0xf bank_mask:0xf
	v_mov_b32_dpp v224, v146 row_ror:8 row_mask:0xf bank_mask:0xf
	v_mov_b32_dpp v225, v147 row_ror:8 row_mask:0xf bank_mask:0xf
	v_mov_b32_dpp v226, v148 row_ror:8 row_mask:0xf bank_mask:0xf
	v_mov_b32_dpp v227, v149 row_ror:8 row_mask:0xf bank_mask:0xf
	v_mov_b32_dpp v228, v150 row_ror:8 row_mask:0xf bank_mask:0xf
	v_mov_b32_dpp v229, v151 row_ror:8 row_mask:0xf bank_mask:0xf
	v_cndmask_b32_e32 v230, v148, v144, vcc
	v_cndmask_b32_e32 v231, v149, v145, vcc
	v_cndmask_b32_e32 v232, v150, v146, vcc
	v_cndmask_b32_e32 v233, v151, v147, vcc
	v_cndmask_b32_e32 v222, v226, v222, vcc
	v_cndmask_b32_e32 v223, v227, v223, vcc
	v_cndmask_b32_e32 v224, v228, v224, vcc
	v_cndmask_b32_e32 v225, v229, v225, vcc
	v_pk_add_f32 v[16:17], v[230:231], v[16:17]
	v_pk_add_f32 v[18:19], v[232:233], v[18:19]
	v_pk_add_f32 v[8:9], v[222:223], v[8:9]
	v_pk_add_f32 v[10:11], v[224:225], v[10:11]
	v_mov_b32_dpp v222, v152 row_ror:8 row_mask:0xf bank_mask:0xf
	v_mov_b32_dpp v223, v153 row_ror:8 row_mask:0xf bank_mask:0xf
	v_mov_b32_dpp v224, v154 row_ror:8 row_mask:0xf bank_mask:0xf
	v_mov_b32_dpp v225, v155 row_ror:8 row_mask:0xf bank_mask:0xf
	v_mov_b32_dpp v226, v156 row_ror:8 row_mask:0xf bank_mask:0xf
	v_mov_b32_dpp v227, v157 row_ror:8 row_mask:0xf bank_mask:0xf
	v_mov_b32_dpp v228, v158 row_ror:8 row_mask:0xf bank_mask:0xf
	v_mov_b32_dpp v229, v159 row_ror:8 row_mask:0xf bank_mask:0xf
	v_cndmask_b32_e32 v230, v156, v152, vcc
	v_cndmask_b32_e32 v231, v157, v153, vcc
	v_cndmask_b32_e32 v232, v158, v154, vcc
	v_cndmask_b32_e32 v233, v159, v155, vcc
	v_cndmask_b32_e32 v222, v226, v222, vcc
	v_cndmask_b32_e32 v223, v227, v223, vcc
	v_cndmask_b32_e32 v224, v228, v224, vcc
	v_cndmask_b32_e32 v225, v229, v225, vcc
	v_pk_add_f32 v[4:5], v[230:231], v[4:5]
	v_pk_add_f32 v[6:7], v[232:233], v[6:7]
	v_pk_add_f32 v[0:1], v[222:223], v[0:1]
	v_pk_add_f32 v[2:3], v[224:225], v[2:3]
	v_add_u32_e32 v236, v193, v234
	v_add_u32_e32 v237, v193, v235
	v_mov_b32_dpp v222, v8 row_ror:8 row_mask:0xf bank_mask:0xf
	v_mov_b32_dpp v223, v9 row_ror:8 row_mask:0xf bank_mask:0xf
	v_mov_b32_dpp v224, v10 row_ror:8 row_mask:0xf bank_mask:0xf
	v_mov_b32_dpp v225, v11 row_ror:8 row_mask:0xf bank_mask:0xf
	v_cndmask_b32_e32 v226, v222, v16, vcc
	v_cndmask_b32_e32 v227, v223, v17, vcc
	v_cndmask_b32_e32 v228, v224, v18, vcc
	v_cndmask_b32_e32 v229, v225, v19, vcc
	v_cndmask_b32_e32 v230, v16, v222, vcc
	v_cndmask_b32_e32 v231, v17, v223, vcc
	v_cndmask_b32_e32 v232, v18, v224, vcc
	v_cndmask_b32_e32 v233, v19, v225, vcc
	global_store_dwordx4 v236, v[226:229], s[72:73] sc1
	global_store_dwordx4 v237, v[230:233], s[72:73] sc1
	v_mov_b32_dpp v222, v0 row_ror:8 row_mask:0xf bank_mask:0xf
	v_mov_b32_dpp v223, v1 row_ror:8 row_mask:0xf bank_mask:0xf
	v_mov_b32_dpp v224, v2 row_ror:8 row_mask:0xf bank_mask:0xf
	v_mov_b32_dpp v225, v3 row_ror:8 row_mask:0xf bank_mask:0xf
	v_cndmask_b32_e32 v226, v222, v4, vcc
	v_cndmask_b32_e32 v227, v223, v5, vcc
	v_cndmask_b32_e32 v228, v224, v6, vcc
	v_cndmask_b32_e32 v229, v225, v7, vcc
	v_cndmask_b32_e32 v230, v4, v222, vcc
	v_cndmask_b32_e32 v231, v5, v223, vcc
	v_cndmask_b32_e32 v232, v6, v224, vcc
	v_cndmask_b32_e32 v233, v7, v225, vcc
	global_store_dwordx4 v236, v[226:229], s[72:73] offset:512 sc1
	global_store_dwordx4 v237, v[230:233], s[72:73] offset:512 sc1
	v_lshrrev_b32_e32 v236, 1, v193
	v_add_u32_e32 v236, v236, v245
	v_cvt_pk_bf16_f32 v194, v16, v17
	v_cvt_pk_bf16_f32 v195, v18, v19
	v_mul_f32_e32 v246, v17, v17
	v_mul_f32_e32 v247, v19, v19
	v_fmac_f32_e32 v246, v16, v16
	v_fmac_f32_e32 v247, v18, v18
	v_add_f32_e32 v187, v246, v247
	v_cvt_pk_bf16_f32 v196, v8, v9
	v_cvt_pk_bf16_f32 v197, v10, v11
	v_mul_f32_e32 v246, v9, v9
	v_mul_f32_e32 v247, v11, v11
	v_fmac_f32_e32 v246, v8, v8
	v_fmac_f32_e32 v247, v10, v10
	v_add_f32_e32 v246, v246, v247
	v_add_f32_e32 v187, v246, v187
	v_permlane16_swap_b32_e32 v194, v196
	v_permlane16_swap_b32_e32 v195, v197
	global_store_dwordx4 v236, v[194:197], s[22:23] sc1
	s_nop 1
	v_cvt_pk_bf16_f32 v194, v4, v5
	v_cvt_pk_bf16_f32 v195, v6, v7
	v_mul_f32_e32 v246, v5, v5
	v_mul_f32_e32 v247, v7, v7
	v_fmac_f32_e32 v246, v4, v4
	v_fmac_f32_e32 v247, v6, v6
	v_add_f32_e32 v246, v246, v247
	v_add_f32_e32 v187, v246, v187
	v_cvt_pk_bf16_f32 v196, v0, v1
	v_cvt_pk_bf16_f32 v197, v2, v3
	v_mul_f32_e32 v246, v1, v1
	v_mul_f32_e32 v247, v3, v3
	v_fmac_f32_e32 v246, v0, v0
	v_fmac_f32_e32 v247, v2, v2
	v_add_f32_e32 v246, v246, v247
	v_add_f32_e32 v187, v246, v187
	v_permlane16_swap_b32_e32 v194, v196
	v_permlane16_swap_b32_e32 v195, v197
	global_store_dwordx4 v236, v[194:197], s[22:23] offset:256 sc1
	s_nop 1
	v_xor_b32_e32 v246, 16, v167
	v_xor_b32_e32 v247, 32, v167
	v_lshlrev_b32_e32 v246, 2, v246
	v_lshlrev_b32_e32 v247, 2, v247
	ds_bpermute_b32 v128, v246, v180
	ds_bpermute_b32 v129, v246, v181
	ds_bpermute_b32 v130, v246, v182
	ds_bpermute_b32 v131, v246, v183
	ds_bpermute_b32 v132, v246, v184
	ds_bpermute_b32 v133, v246, v185
	ds_bpermute_b32 v134, v246, v186
	ds_bpermute_b32 v135, v246, v187
	s_waitcnt lgkmcnt(0)
	v_add_f32_e32 v180, v180, v128
	v_add_f32_e32 v181, v181, v129
	v_add_f32_e32 v182, v182, v130
	v_add_f32_e32 v183, v183, v131
	v_add_f32_e32 v184, v184, v132
	v_add_f32_e32 v185, v185, v133
	v_add_f32_e32 v186, v186, v134
	v_add_f32_e32 v187, v187, v135
	ds_bpermute_b32 v128, v247, v180
	ds_bpermute_b32 v129, v247, v181
	ds_bpermute_b32 v130, v247, v182
	ds_bpermute_b32 v131, v247, v183
	ds_bpermute_b32 v132, v247, v184
	ds_bpermute_b32 v133, v247, v185
	ds_bpermute_b32 v134, v247, v186
	ds_bpermute_b32 v135, v247, v187
	s_waitcnt lgkmcnt(0)
	v_add_f32_e32 v180, v180, v128
	v_add_f32_e32 v181, v181, v129
	v_add_f32_e32 v182, v182, v130
	v_add_f32_e32 v183, v183, v131
	v_add_f32_e32 v184, v184, v132
	v_add_f32_e32 v185, v185, v133
	v_add_f32_e32 v186, v186, v134
	v_add_f32_e32 v187, v187, v135
	v_add_u32_e32 v136, 0x0, v189
	v_add_u32_e32 v137, 0x800, v189
	v_add_u32_e32 v138, 0x1000, v189
	v_add_u32_e32 v139, 0x1800, v189
	v_add_u32_e32 v140, 0x4000, v189
	v_add_u32_e32 v141, 0x4800, v189
	v_add_u32_e32 v142, 0x5000, v189
	v_add_u32_e32 v143, 0x5800, v189
	s_and_saveexec_b64 s[36:37], s[0:1]
	global_store_dword v136, v180, s[10:11]
	global_store_dword v137, v181, s[10:11]
	global_store_dword v138, v182, s[10:11]
	global_store_dword v139, v183, s[10:11]
	global_store_dword v140, v184, s[10:11]
	global_store_dword v141, v185, s[10:11]
	global_store_dword v142, v186, s[10:11]
	global_store_dword v143, v187, s[10:11]
	s_or_b64 exec, exec, s[36:37]
	s_branch .LBB0_385
;     __device__ __forceinline__ void operator()(const f32x4 (&acc)[2][2][4][2], const Unit& u, int wr, int wc, int fr, int fq) const {
;         const int row0 = u.pm * BM + wr * 64 + fr, col0 = u.pn * BM + wc * 32 + 4 * fq;
;         f32x4 bs[2][4];
; #pragma unroll
;         for (int q = 0; q < 4; ++q) bs[0][q] = *(const f32x4*)(xin + (size_t)row0 * ldc + col0 + (q >> 1) * HALF + (q & 1) * 16);
; #pragma unroll
;         for (int gi = 0; gi < 8; ++gi) {
;             const int ai = gi >> 2, m = gi & 3;
;             const int row = row0 + ai * HALF + m * 16;
;             const size_t off = (size_t)row * ldc + col0;
;             if (gi + 1 < 8) {
;                 const size_t offn = (size_t)(row0 + ((gi + 1) >> 2) * HALF + ((gi + 1) & 3) * 16) * ldc + col0;
; #pragma unroll
;                 for (int q = 0; q < 4; ++q) bs[(gi + 1) & 1][q] = *(const f32x4*)(xin + offn + (q >> 1) * HALF + (q & 1) * 16);
;             }
;             float sq = 0.f;
; #pragma unroll
;             for (int q = 0; q < 4; ++q) {
;                 const int bj = q >> 1, n = q & 1;
;                 const f32x4 o = bs[gi & 1][q] + acc[ai][bj][m][n];
;                 *(f32x4*)(out + off + bj * HALF + n * 16) = o;
.Lres_noss:
	v_lshl_add_u32 v246, s55, 8, v188
	v_lshl_or_b32 v247, s2, 8, v190
	v_lshlrev_b32_e32 v247, 2, v247
	v_lshl_add_u32 v160, v246, 13, v247
	v_add_u32_e32 v161, 0x20000, v160
	v_add_u32_e32 v162, 0x40000, v160
	v_add_u32_e32 v163, 0x60000, v160
	v_add_u32_e32 v164, 0x100000, v160
	v_add_u32_e32 v165, 0x120000, v160
	v_add_u32_e32 v192, 0x140000, v160
	v_add_u32_e32 v193, 0x160000, v160
	v_and_b32_e32 v246, 8, v188
	v_mov_b32_e32 v247, 0x10040
	v_cmp_eq_u32_e32 vcc, 0, v246
	v_mov_b32_e32 v246, 0xffff0040
	s_nop 0
	v_cndmask_b32_e32 v234, v246, v169, vcc
	v_cndmask_b32_e32 v235, 0, v247, vcc
	v_add_u32_e32 v236, v160, v234
	v_add_u32_e32 v237, v160, v235
	global_load_dwordx4 v[128:131], v236, s[14:15]
	global_load_dwordx4 v[132:135], v237, s[14:15]
	global_load_dwordx4 v[136:139], v236, s[14:15] offset:512
	global_load_dwordx4 v[140:143], v237, s[14:15] offset:512
	v_add_u32_e32 v236, v161, v234
	v_add_u32_e32 v237, v161, v235
	global_load_dwordx4 v[144:147], v236, s[14:15]
	global_load_dwordx4 v[148:151], v237, s[14:15]
	global_load_dwordx4 v[152:155], v236, s[14:15] offset:512
	global_load_dwordx4 v[156:159], v237, s[14:15] offset:512
	v_add_u32_e32 v236, v162, v234
	v_add_u32_e32 v237, v162, v235
	global_load_dwordx4 v[206:209], v236, s[14:15]
	global_load_dwordx4 v[210:213], v237, s[14:15]
	global_load_dwordx4 v[214:217], v236, s[14:15] offset:512
	global_load_dwordx4 v[218:221], v237, s[14:15] offset:512
	s_waitcnt vmcnt(8)
	v_mov_b32_dpp v222, v128 row_ror:8 row_mask:0xf bank_mask:0xf
	v_mov_b32_dpp v223, v129 row_ror:8 row_mask:0xf bank_mask:0xf
	v_mov_b32_dpp v224, v130 row_ror:8 row_mask:0xf bank_mask:0xf
	v_mov_b32_dpp v225, v131 row_ror:8 row_mask:0xf bank_mask:0xf
	v_mov_b32_dpp v226, v132 row_ror:8 row_mask:0xf bank_mask:0xf
	v_mov_b32_dpp v227, v133 row_ror:8 row_mask:0xf bank_mask:0xf
	v_mov_b32_dpp v228, v134 row_ror:8 row_mask:0xf bank_mask:0xf
	v_mov_b32_dpp v229, v135 row_ror:8 row_mask:0xf bank_mask:0xf
	v_cndmask_b32_e32 v230, v132, v128, vcc
	v_cndmask_b32_e32 v231, v133, v129, vcc
	v_cndmask_b32_e32 v232, v134, v130, vcc
	v_cndmask_b32_e32 v233, v135, v131, vcc
	v_cndmask_b32_e32 v222, v226, v222, vcc
	v_cndmask_b32_e32 v223, v227, v223, vcc
	v_cndmask_b32_e32 v224, v228, v224, vcc
	v_cndmask_b32_e32 v225, v229, v225, vcc
	v_pk_add_f32 v[124:125], v[230:231], v[124:125]
	v_pk_add_f32 v[126:127], v[232:233], v[126:127]
	v_pk_add_f32 v[120:121], v[222:223], v[120:121]
	v_pk_add_f32 v[122:123], v[224:225], v[122:123]
	v_mov_b32_dpp v222, v136 row_ror:8 row_mask:0xf bank_mask:0xf
	v_mov_b32_dpp v223, v137 row_ror:8 row_mask:0xf bank_mask:0xf
	v_mov_b32_dpp v224, v138 row_ror:8 row_mask:0xf bank_mask:0xf
	v_mov_b32_dpp v225, v139 row_ror:8 row_mask:0xf bank_mask:0xf
	v_mov_b32_dpp v226, v140 row_ror:8 row_mask:0xf bank_mask:0xf
	v_mov_b32_dpp v227, v141 row_ror:8 row_mask:0xf bank_mask:0xf
	v_mov_b32_dpp v228, v142 row_ror:8 row_mask:0xf bank_mask:0xf
	v_mov_b32_dpp v229, v143 row_ror:8 row_mask:0xf bank_mask:0xf
	v_cndmask_b32_e32 v230, v140, v136, vcc
	v_cndmask_b32_e32 v231, v141, v137, vcc
	v_cndmask_b32_e32 v232, v142, v138, vcc
	v_cndmask_b32_e32 v233, v143, v139, vcc
	v_cndmask_b32_e32 v222, v226, v222, vcc
	v_cndmask_b32_e32 v223, v227, v223, vcc
	v_cndmask_b32_e32 v224, v228, v224, vcc
	v_cndmask_b32_e32 v225, v229, v225, vcc
	v_pk_add_f32 v[116:117], v[230:231], v[116:117]
	v_pk_add_f32 v[118:119], v[232:233], v[118:119]
	v_pk_add_f32 v[108:109], v[222:223], v[108:109]
	v_pk_add_f32 v[110:111], v[224:225], v[110:111]
	v_add_u32_e32 v236, v163, v234
	v_add_u32_e32 v237, v163, v235
	global_load_dwordx4 v[128:131], v236, s[14:15]
	global_load_dwordx4 v[132:135], v237, s[14:15]
	global_load_dwordx4 v[136:139], v236, s[14:15] offset:512
	global_load_dwordx4 v[140:143], v237, s[14:15] offset:512
	v_add_u32_e32 v236, v160, v234
	v_add_u32_e32 v237, v160, v235
	v_mov_b32_dpp v222, v120 row_ror:8 row_mask:0xf bank_mask:0xf
	v_mov_b32_dpp v223, v121 row_ror:8 row_mask:0xf bank_mask:0xf
	v_mov_b32_dpp v224, v122 row_ror:8 row_mask:0xf bank_mask:0xf
	v_mov_b32_dpp v225, v123 row_ror:8 row_mask:0xf bank_mask:0xf
	v_cndmask_b32_e32 v226, v222, v124, vcc
	v_cndmask_b32_e32 v227, v223, v125, vcc
	v_cndmask_b32_e32 v228, v224, v126, vcc
	v_cndmask_b32_e32 v229, v225, v127, vcc
	v_cndmask_b32_e32 v230, v124, v222, vcc
	v_cndmask_b32_e32 v231, v125, v223, vcc
	v_cndmask_b32_e32 v232, v126, v224, vcc
	v_cndmask_b32_e32 v233, v127, v225, vcc
	global_store_dwordx4 v236, v[226:229], s[72:73] sc1
	global_store_dwordx4 v237, v[230:233], s[72:73] sc1
	v_mov_b32_dpp v222, v108 row_ror:8 row_mask:0xf bank_mask:0xf
	v_mov_b32_dpp v223, v109 row_ror:8 row_mask:0xf bank_mask:0xf
	v_mov_b32_dpp v224, v110 row_ror:8 row_mask:0xf bank_mask:0xf
	v_mov_b32_dpp v225, v111 row_ror:8 row_mask:0xf bank_mask:0xf
	v_cndmask_b32_e32 v226, v222, v116, vcc
	v_cndmask_b32_e32 v227, v223, v117, vcc
	v_cndmask_b32_e32 v228, v224, v118, vcc
	v_cndmask_b32_e32 v229, v225, v119, vcc
	v_cndmask_b32_e32 v230, v116, v222, vcc
	v_cndmask_b32_e32 v231, v117, v223, vcc
	v_cndmask_b32_e32 v232, v118, v224, vcc
	v_cndmask_b32_e32 v233, v119, v225, vcc
	global_store_dwordx4 v236, v[226:229], s[72:73] offset:512 sc1
	global_store_dwordx4 v237, v[230:233], s[72:73] offset:512 sc1
	s_waitcnt vmcnt(12)
;     __device__ __forceinline__ void operator()(const f32x4 (&acc)[2][2][4][2], const Unit& u, int wr, int wc, int fr, int fq) const {
;     ...
; #pragma unroll
;         for (int gi = 0; gi < 8; ++gi) {
;             const int ai = gi >> 2, m = gi & 3;
;             const int row = row0 + ai * HALF + m * 16;
;             const size_t off = (size_t)row * ldc + col0;
;             if (gi + 1 < 8) {
;                 const size_t offn = (size_t)(row0 + ((gi + 1) >> 2) * HALF + ((gi + 1) & 3) * 16) * ldc + col0;
; #pragma unroll
;                 for (int q = 0; q < 4; ++q) bs[(gi + 1) & 1][q] = *(const f32x4*)(xin + offn + (q >> 1) * HALF + (q & 1) * 16);
;             }
;             float sq = 0.f;
; #pragma unroll
;             for (int q = 0; q < 4; ++q) {
;                 const int bj = q >> 1, n = q & 1;
;                 const f32x4 o = bs[gi & 1][q] + acc[ai][bj][m][n];
;                 *(f32x4*)(out + off + bj * HALF + n * 16) = o;
	v_mov_b32_dpp v222, v144 row_ror:8 row_mask:0xf bank_mask:0xf
	v_mov_b32_dpp v223, v145 row_ror:8 row_mask:0xf bank_mask:0xf
	v_mov_b32_dpp v224, v146 row_ror:8 row_mask:0xf bank_mask:0xf
	v_mov_b32_dpp v225, v147 row_ror:8 row_mask:0xf bank_mask:0xf
	v_mov_b32_dpp v226, v148 row_ror:8 row_mask:0xf bank_mask:0xf
	v_mov_b32_dpp v227, v149 row_ror:8 row_mask:0xf bank_mask:0xf
	v_mov_b32_dpp v228, v150 row_ror:8 row_mask:0xf bank_mask:0xf
	v_mov_b32_dpp v229, v151 row_ror:8 row_mask:0xf bank_mask:0xf
	v_cndmask_b32_e32 v230, v148, v144, vcc
	v_cndmask_b32_e32 v231, v149, v145, vcc
	v_cndmask_b32_e32 v232, v150, v146, vcc
	v_cndmask_b32_e32 v233, v151, v147, vcc
	v_cndmask_b32_e32 v222, v226, v222, vcc
	v_cndmask_b32_e32 v223, v227, v223, vcc
	v_cndmask_b32_e32 v224, v228, v224, vcc
	v_cndmask_b32_e32 v225, v229, v225, vcc
	v_pk_add_f32 v[112:113], v[230:231], v[112:113]
	v_pk_add_f32 v[114:115], v[232:233], v[114:115]
	v_pk_add_f32 v[104:105], v[222:223], v[104:105]
	v_pk_add_f32 v[106:107], v[224:225], v[106:107]
	v_mov_b32_dpp v222, v152 row_ror:8 row_mask:0xf bank_mask:0xf
	v_mov_b32_dpp v223, v153 row_ror:8 row_mask:0xf bank_mask:0xf
	v_mov_b32_dpp v224, v154 row_ror:8 row_mask:0xf bank_mask:0xf
	v_mov_b32_dpp v225, v155 row_ror:8 row_mask:0xf bank_mask:0xf
	v_mov_b32_dpp v226, v156 row_ror:8 row_mask:0xf bank_mask:0xf
	v_mov_b32_dpp v227, v157 row_ror:8 row_mask:0xf bank_mask:0xf
	v_mov_b32_dpp v228, v158 row_ror:8 row_mask:0xf bank_mask:0xf
	v_mov_b32_dpp v229, v159 row_ror:8 row_mask:0xf bank_mask:0xf
	v_cndmask_b32_e32 v230, v156, v152, vcc
	v_cndmask_b32_e32 v231, v157, v153, vcc
	v_cndmask_b32_e32 v232, v158, v154, vcc
	v_cndmask_b32_e32 v233, v159, v155, vcc
	v_cndmask_b32_e32 v222, v226, v222, vcc
	v_cndmask_b32_e32 v223, v227, v223, vcc
	v_cndmask_b32_e32 v224, v228, v224, vcc
	v_cndmask_b32_e32 v225, v229, v225, vcc
	v_pk_add_f32 v[100:101], v[230:231], v[100:101]
	v_pk_add_f32 v[102:103], v[232:233], v[102:103]
	v_pk_add_f32 v[92:93], v[222:223], v[92:93]
	v_pk_add_f32 v[94:95], v[224:225], v[94:95]
	v_add_u32_e32 v236, v164, v234
	v_add_u32_e32 v237, v164, v235
	global_load_dwordx4 v[144:147], v236, s[14:15]
	global_load_dwordx4 v[148:151], v237, s[14:15]
	global_load_dwordx4 v[152:155], v236, s[14:15] offset:512
	global_load_dwordx4 v[156:159], v237, s[14:15] offset:512
	v_add_u32_e32 v236, v161, v234
	v_add_u32_e32 v237, v161, v235
	v_mov_b32_dpp v222, v104 row_ror:8 row_mask:0xf bank_mask:0xf
	v_mov_b32_dpp v223, v105 row_ror:8 row_mask:0xf bank_mask:0xf
	v_mov_b32_dpp v224, v106 row_ror:8 row_mask:0xf bank_mask:0xf
	v_mov_b32_dpp v225, v107 row_ror:8 row_mask:0xf bank_mask:0xf
	v_cndmask_b32_e32 v226, v222, v112, vcc
	v_cndmask_b32_e32 v227, v223, v113, vcc
	v_cndmask_b32_e32 v228, v224, v114, vcc
	v_cndmask_b32_e32 v229, v225, v115, vcc
	v_cndmask_b32_e32 v230, v112, v222, vcc
	v_cndmask_b32_e32 v231, v113, v223, vcc
	v_cndmask_b32_e32 v232, v114, v224, vcc
	v_cndmask_b32_e32 v233, v115, v225, vcc
	global_store_dwordx4 v236, v[226:229], s[72:73] sc1
	global_store_dwordx4 v237, v[230:233], s[72:73] sc1
	v_mov_b32_dpp v222, v92 row_ror:8 row_mask:0xf bank_mask:0xf
	v_mov_b32_dpp v223, v93 row_ror:8 row_mask:0xf bank_mask:0xf
	v_mov_b32_dpp v224, v94 row_ror:8 row_mask:0xf bank_mask:0xf
	v_mov_b32_dpp v225, v95 row_ror:8 row_mask:0xf bank_mask:0xf
	v_cndmask_b32_e32 v226, v222, v100, vcc
	v_cndmask_b32_e32 v227, v223, v101, vcc
	v_cndmask_b32_e32 v228, v224, v102, vcc
	v_cndmask_b32_e32 v229, v225, v103, vcc
	v_cndmask_b32_e32 v230, v100, v222, vcc
	v_cndmask_b32_e32 v231, v101, v223, vcc
	v_cndmask_b32_e32 v232, v102, v224, vcc
	v_cndmask_b32_e32 v233, v103, v225, vcc
	global_store_dwordx4 v236, v[226:229], s[72:73] offset:512 sc1
	global_store_dwordx4 v237, v[230:233], s[72:73] offset:512 sc1
	s_waitcnt vmcnt(16)
	v_mov_b32_dpp v222, v206 row_ror:8 row_mask:0xf bank_mask:0xf
	v_mov_b32_dpp v223, v207 row_ror:8 row_mask:0xf bank_mask:0xf
	v_mov_b32_dpp v224, v208 row_ror:8 row_mask:0xf bank_mask:0xf
	v_mov_b32_dpp v225, v209 row_ror:8 row_mask:0xf bank_mask:0xf
	v_mov_b32_dpp v226, v210 row_ror:8 row_mask:0xf bank_mask:0xf
	v_mov_b32_dpp v227, v211 row_ror:8 row_mask:0xf bank_mask:0xf
	v_mov_b32_dpp v228, v212 row_ror:8 row_mask:0xf bank_mask:0xf
	v_mov_b32_dpp v229, v213 row_ror:8 row_mask:0xf bank_mask:0xf
	v_cndmask_b32_e32 v230, v210, v206, vcc
	v_cndmask_b32_e32 v231, v211, v207, vcc
	v_cndmask_b32_e32 v232, v212, v208, vcc
	v_cndmask_b32_e32 v233, v213, v209, vcc
	v_cndmask_b32_e32 v222, v226, v222, vcc
	v_cndmask_b32_e32 v223, v227, v223, vcc
	v_cndmask_b32_e32 v224, v228, v224, vcc
	v_cndmask_b32_e32 v225, v229, v225, vcc
	v_pk_add_f32 v[96:97], v[230:231], v[96:97]
	v_pk_add_f32 v[98:99], v[232:233], v[98:99]
	v_pk_add_f32 v[88:89], v[222:223], v[88:89]
	v_pk_add_f32 v[90:91], v[224:225], v[90:91]
	v_mov_b32_dpp v222, v214 row_ror:8 row_mask:0xf bank_mask:0xf
	v_mov_b32_dpp v223, v215 row_ror:8 row_mask:0xf bank_mask:0xf
	v_mov_b32_dpp v224, v216 row_ror:8 row_mask:0xf bank_mask:0xf
	v_mov_b32_dpp v225, v217 row_ror:8 row_mask:0xf bank_mask:0xf
	v_mov_b32_dpp v226, v218 row_ror:8 row_mask:0xf bank_mask:0xf
	v_mov_b32_dpp v227, v219 row_ror:8 row_mask:0xf bank_mask:0xf
	v_mov_b32_dpp v228, v220 row_ror:8 row_mask:0xf bank_mask:0xf
	v_mov_b32_dpp v229, v221 row_ror:8 row_mask:0xf bank_mask:0xf
	v_cndmask_b32_e32 v230, v218, v214, vcc
	v_cndmask_b32_e32 v231, v219, v215, vcc
	v_cndmask_b32_e32 v232, v220, v216, vcc
	v_cndmask_b32_e32 v233, v221, v217, vcc
	v_cndmask_b32_e32 v222, v226, v222, vcc
	v_cndmask_b32_e32 v223, v227, v223, vcc
	v_cndmask_b32_e32 v224, v228, v224, vcc
	v_cndmask_b32_e32 v225, v229, v225, vcc
; __device__ __forceinline__ unsigned cvt_pk_bf16(float lo, float hi) { unsigned r; asm volatile("v_cvt_pk_bf16_f32 %0, %1, %2" : "=v"(r) : "v"(lo), "v"(hi)); return r; }
;     __device__ __forceinline__ void operator()(const f32x4 (&acc)[2][2][4][2], const Unit& u, int wr, int wc, int fr, int fq) const {
;     ...
;         for (int gi = 0; gi < 8; ++gi) {
;             const int ai = gi >> 2, m = gi & 3;
;             const int row = row0 + ai * HALF + m * 16;
;             const size_t off = (size_t)row * ldc + col0;
;             if (gi + 1 < 8) {
;                 const size_t offn = (size_t)(row0 + ((gi + 1) >> 2) * HALF + ((gi + 1) & 3) * 16) * ldc + col0;
; #pragma unroll
;                 for (int q = 0; q < 4; ++q) bs[(gi + 1) & 1][q] = *(const f32x4*)(xin + offn + (q >> 1) * HALF + (q & 1) * 16);
;             }
;             float sq = 0.f;
; #pragma unroll
;             for (int q = 0; q < 4; ++q) {
;                 const int bj = q >> 1, n = q & 1;
;                 const f32x4 o = bs[gi & 1][q] + acc[ai][bj][m][n];
;                 *(f32x4*)(out + off + bj * HALF + n * 16) = o;
;                 if (ss) {
;                     u32x2 w; w.x = cvt_pk_bf16(o[0], o[1]); w.y = cvt_pk_bf16(o[2], o[3]);
;                     *(u32x2*)(xb + off + bj * HALF + n * 16) = w;
;                     sq += (o[0] * o[0] + o[1] * o[1]) + (o[2] * o[2] + o[3] * o[3]);
;                 }
;             }
	v_pk_add_f32 v[84:85], v[230:231], v[84:85]
	v_pk_add_f32 v[86:87], v[232:233], v[86:87]
	v_pk_add_f32 v[76:77], v[222:223], v[76:77]
	v_pk_add_f32 v[78:79], v[224:225], v[78:79]
	v_add_u32_e32 v236, v165, v234
	v_add_u32_e32 v237, v165, v235
	global_load_dwordx4 v[206:209], v236, s[14:15]
	global_load_dwordx4 v[210:213], v237, s[14:15]
	global_load_dwordx4 v[214:217], v236, s[14:15] offset:512
	global_load_dwordx4 v[218:221], v237, s[14:15] offset:512
	v_add_u32_e32 v236, v162, v234
	v_add_u32_e32 v237, v162, v235
	v_mov_b32_dpp v222, v88 row_ror:8 row_mask:0xf bank_mask:0xf
	v_mov_b32_dpp v223, v89 row_ror:8 row_mask:0xf bank_mask:0xf
	v_mov_b32_dpp v224, v90 row_ror:8 row_mask:0xf bank_mask:0xf
	v_mov_b32_dpp v225, v91 row_ror:8 row_mask:0xf bank_mask:0xf
	v_cndmask_b32_e32 v226, v222, v96, vcc
	v_cndmask_b32_e32 v227, v223, v97, vcc
	v_cndmask_b32_e32 v228, v224, v98, vcc
	v_cndmask_b32_e32 v229, v225, v99, vcc
	v_cndmask_b32_e32 v230, v96, v222, vcc
	v_cndmask_b32_e32 v231, v97, v223, vcc
	v_cndmask_b32_e32 v232, v98, v224, vcc
	v_cndmask_b32_e32 v233, v99, v225, vcc
	global_store_dwordx4 v236, v[226:229], s[72:73] sc1
	global_store_dwordx4 v237, v[230:233], s[72:73] sc1
	v_mov_b32_dpp v222, v76 row_ror:8 row_mask:0xf bank_mask:0xf
	v_mov_b32_dpp v223, v77 row_ror:8 row_mask:0xf bank_mask:0xf
	v_mov_b32_dpp v224, v78 row_ror:8 row_mask:0xf bank_mask:0xf
	v_mov_b32_dpp v225, v79 row_ror:8 row_mask:0xf bank_mask:0xf
	v_cndmask_b32_e32 v226, v222, v84, vcc
	v_cndmask_b32_e32 v227, v223, v85, vcc
	v_cndmask_b32_e32 v228, v224, v86, vcc
	v_cndmask_b32_e32 v229, v225, v87, vcc
	v_cndmask_b32_e32 v230, v84, v222, vcc
	v_cndmask_b32_e32 v231, v85, v223, vcc
	v_cndmask_b32_e32 v232, v86, v224, vcc
	v_cndmask_b32_e32 v233, v87, v225, vcc
	global_store_dwordx4 v236, v[226:229], s[72:73] offset:512 sc1
	global_store_dwordx4 v237, v[230:233], s[72:73] offset:512 sc1
	s_waitcnt vmcnt(20)
	v_mov_b32_dpp v222, v128 row_ror:8 row_mask:0xf bank_mask:0xf
	v_mov_b32_dpp v223, v129 row_ror:8 row_mask:0xf bank_mask:0xf
	v_mov_b32_dpp v224, v130 row_ror:8 row_mask:0xf bank_mask:0xf
	v_mov_b32_dpp v225, v131 row_ror:8 row_mask:0xf bank_mask:0xf
	v_mov_b32_dpp v226, v132 row_ror:8 row_mask:0xf bank_mask:0xf
	v_mov_b32_dpp v227, v133 row_ror:8 row_mask:0xf bank_mask:0xf
	v_mov_b32_dpp v228, v134 row_ror:8 row_mask:0xf bank_mask:0xf
	v_mov_b32_dpp v229, v135 row_ror:8 row_mask:0xf bank_mask:0xf
	v_cndmask_b32_e32 v230, v132, v128, vcc
	v_cndmask_b32_e32 v231, v133, v129, vcc
	v_cndmask_b32_e32 v232, v134, v130, vcc
	v_cndmask_b32_e32 v233, v135, v131, vcc
	v_cndmask_b32_e32 v222, v226, v222, vcc
	v_cndmask_b32_e32 v223, v227, v223, vcc
	v_cndmask_b32_e32 v224, v228, v224, vcc
	v_cndmask_b32_e32 v225, v229, v225, vcc
	v_pk_add_f32 v[80:81], v[230:231], v[80:81]
	v_pk_add_f32 v[82:83], v[232:233], v[82:83]
	v_pk_add_f32 v[72:73], v[222:223], v[72:73]
	v_pk_add_f32 v[74:75], v[224:225], v[74:75]
	v_mov_b32_dpp v222, v136 row_ror:8 row_mask:0xf bank_mask:0xf
	v_mov_b32_dpp v223, v137 row_ror:8 row_mask:0xf bank_mask:0xf
	v_mov_b32_dpp v224, v138 row_ror:8 row_mask:0xf bank_mask:0xf
	v_mov_b32_dpp v225, v139 row_ror:8 row_mask:0xf bank_mask:0xf
	v_mov_b32_dpp v226, v140 row_ror:8 row_mask:0xf bank_mask:0xf
	v_mov_b32_dpp v227, v141 row_ror:8 row_mask:0xf bank_mask:0xf
	v_mov_b32_dpp v228, v142 row_ror:8 row_mask:0xf bank_mask:0xf
	v_mov_b32_dpp v229, v143 row_ror:8 row_mask:0xf bank_mask:0xf
	v_cndmask_b32_e32 v230, v140, v136, vcc
	v_cndmask_b32_e32 v231, v141, v137, vcc
	v_cndmask_b32_e32 v232, v142, v138, vcc
	v_cndmask_b32_e32 v233, v143, v139, vcc
	v_cndmask_b32_e32 v222, v226, v222, vcc
	v_cndmask_b32_e32 v223, v227, v223, vcc
	v_cndmask_b32_e32 v224, v228, v224, vcc
	v_cndmask_b32_e32 v225, v229, v225, vcc
	v_pk_add_f32 v[68:69], v[230:231], v[68:69]
	v_pk_add_f32 v[70:71], v[232:233], v[70:71]
	v_pk_add_f32 v[64:65], v[222:223], v[64:65]
	v_pk_add_f32 v[66:67], v[224:225], v[66:67]
	v_add_u32_e32 v236, v192, v234
	v_add_u32_e32 v237, v192, v235
	global_load_dwordx4 v[128:131], v236, s[14:15]
	global_load_dwordx4 v[132:135], v237, s[14:15]
	global_load_dwordx4 v[136:139], v236, s[14:15] offset:512
	global_load_dwordx4 v[140:143], v237, s[14:15] offset:512
	v_add_u32_e32 v236, v163, v234
	v_add_u32_e32 v237, v163, v235
	v_mov_b32_dpp v222, v72 row_ror:8 row_mask:0xf bank_mask:0xf
	v_mov_b32_dpp v223, v73 row_ror:8 row_mask:0xf bank_mask:0xf
	v_mov_b32_dpp v224, v74 row_ror:8 row_mask:0xf bank_mask:0xf
	v_mov_b32_dpp v225, v75 row_ror:8 row_mask:0xf bank_mask:0xf
	v_cndmask_b32_e32 v226, v222, v80, vcc
	v_cndmask_b32_e32 v227, v223, v81, vcc
	v_cndmask_b32_e32 v228, v224, v82, vcc
	v_cndmask_b32_e32 v229, v225, v83, vcc
	v_cndmask_b32_e32 v230, v80, v222, vcc
	v_cndmask_b32_e32 v231, v81, v223, vcc
	v_cndmask_b32_e32 v232, v82, v224, vcc
	v_cndmask_b32_e32 v233, v83, v225, vcc
	global_store_dwordx4 v236, v[226:229], s[72:73] sc1
	global_store_dwordx4 v237, v[230:233], s[72:73] sc1
	v_mov_b32_dpp v222, v64 row_ror:8 row_mask:0xf bank_mask:0xf
	v_mov_b32_dpp v223, v65 row_ror:8 row_mask:0xf bank_mask:0xf
	v_mov_b32_dpp v224, v66 row_ror:8 row_mask:0xf bank_mask:0xf
	v_mov_b32_dpp v225, v67 row_ror:8 row_mask:0xf bank_mask:0xf
	v_cndmask_b32_e32 v226, v222, v68, vcc
	v_cndmask_b32_e32 v227, v223, v69, vcc
	v_cndmask_b32_e32 v228, v224, v70, vcc
	v_cndmask_b32_e32 v229, v225, v71, vcc
	v_cndmask_b32_e32 v230, v68, v222, vcc
	v_cndmask_b32_e32 v231, v69, v223, vcc
	v_cndmask_b32_e32 v232, v70, v224, vcc
	v_cndmask_b32_e32 v233, v71, v225, vcc
	global_store_dwordx4 v236, v[226:229], s[72:73] offset:512 sc1
	global_store_dwordx4 v237, v[230:233], s[72:73] offset:512 sc1
	s_waitcnt vmcnt(20)
; __device__ __forceinline__ unsigned cvt_pk_bf16(float lo, float hi) { unsigned r; asm volatile("v_cvt_pk_bf16_f32 %0, %1, %2" : "=v"(r) : "v"(lo), "v"(hi)); return r; }
;     __device__ __forceinline__ void operator()(const f32x4 (&acc)[2][2][4][2], const Unit& u, int wr, int wc, int fr, int fq) const {
;     ...
;         for (int gi = 0; gi < 8; ++gi) {
;             const int ai = gi >> 2, m = gi & 3;
;             const int row = row0 + ai * HALF + m * 16;
;             const size_t off = (size_t)row * ldc + col0;
;             if (gi + 1 < 8) {
;                 const size_t offn = (size_t)(row0 + ((gi + 1) >> 2) * HALF + ((gi + 1) & 3) * 16) * ldc + col0;
; #pragma unroll
;                 for (int q = 0; q < 4; ++q) bs[(gi + 1) & 1][q] = *(const f32x4*)(xin + offn + (q >> 1) * HALF + (q & 1) * 16);
;             }
;             float sq = 0.f;
; #pragma unroll
;             for (int q = 0; q < 4; ++q) {
;                 const int bj = q >> 1, n = q & 1;
;                 const f32x4 o = bs[gi & 1][q] + acc[ai][bj][m][n];
;                 *(f32x4*)(out + off + bj * HALF + n * 16) = o;
;                 if (ss) {
;                     u32x2 w; w.x = cvt_pk_bf16(o[0], o[1]); w.y = cvt_pk_bf16(o[2], o[3]);
;                     *(u32x2*)(xb + off + bj * HALF + n * 16) = w;
;                     sq += (o[0] * o[0] + o[1] * o[1]) + (o[2] * o[2] + o[3] * o[3]);
;                 }
;             }
	v_mov_b32_dpp v222, v144 row_ror:8 row_mask:0xf bank_mask:0xf
	v_mov_b32_dpp v223, v145 row_ror:8 row_mask:0xf bank_mask:0xf
	v_mov_b32_dpp v224, v146 row_ror:8 row_mask:0xf bank_mask:0xf
	v_mov_b32_dpp v225, v147 row_ror:8 row_mask:0xf bank_mask:0xf
	v_mov_b32_dpp v226, v148 row_ror:8 row_mask:0xf bank_mask:0xf
	v_mov_b32_dpp v227, v149 row_ror:8 row_mask:0xf bank_mask:0xf
	v_mov_b32_dpp v228, v150 row_ror:8 row_mask:0xf bank_mask:0xf
	v_mov_b32_dpp v229, v151 row_ror:8 row_mask:0xf bank_mask:0xf
	v_cndmask_b32_e32 v230, v148, v144, vcc
	v_cndmask_b32_e32 v231, v149, v145, vcc
	v_cndmask_b32_e32 v232, v150, v146, vcc
	v_cndmask_b32_e32 v233, v151, v147, vcc
	v_cndmask_b32_e32 v222, v226, v222, vcc
	v_cndmask_b32_e32 v223, v227, v223, vcc
	v_cndmask_b32_e32 v224, v228, v224, vcc
	v_cndmask_b32_e32 v225, v229, v225, vcc
	v_pk_add_f32 v[60:61], v[230:231], v[60:61]
	v_pk_add_f32 v[62:63], v[232:233], v[62:63]
	v_pk_add_f32 v[56:57], v[222:223], v[56:57]
	v_pk_add_f32 v[58:59], v[224:225], v[58:59]
	v_mov_b32_dpp v222, v152 row_ror:8 row_mask:0xf bank_mask:0xf
	v_mov_b32_dpp v223, v153 row_ror:8 row_mask:0xf bank_mask:0xf
	v_mov_b32_dpp v224, v154 row_ror:8 row_mask:0xf bank_mask:0xf
	v_mov_b32_dpp v225, v155 row_ror:8 row_mask:0xf bank_mask:0xf
	v_mov_b32_dpp v226, v156 row_ror:8 row_mask:0xf bank_mask:0xf
	v_mov_b32_dpp v227, v157 row_ror:8 row_mask:0xf bank_mask:0xf
	v_mov_b32_dpp v228, v158 row_ror:8 row_mask:0xf bank_mask:0xf
	v_mov_b32_dpp v229, v159 row_ror:8 row_mask:0xf bank_mask:0xf
	v_cndmask_b32_e32 v230, v156, v152, vcc
	v_cndmask_b32_e32 v231, v157, v153, vcc
	v_cndmask_b32_e32 v232, v158, v154, vcc
	v_cndmask_b32_e32 v233, v159, v155, vcc
	v_cndmask_b32_e32 v222, v226, v222, vcc
	v_cndmask_b32_e32 v223, v227, v223, vcc
	v_cndmask_b32_e32 v224, v228, v224, vcc
	v_cndmask_b32_e32 v225, v229, v225, vcc
	v_pk_add_f32 v[52:53], v[230:231], v[52:53]
	v_pk_add_f32 v[54:55], v[232:233], v[54:55]
	v_pk_add_f32 v[44:45], v[222:223], v[44:45]
	v_pk_add_f32 v[46:47], v[224:225], v[46:47]
	v_add_u32_e32 v236, v193, v234
	v_add_u32_e32 v237, v193, v235
	global_load_dwordx4 v[144:147], v236, s[14:15]
	global_load_dwordx4 v[148:151], v237, s[14:15]
	global_load_dwordx4 v[152:155], v236, s[14:15] offset:512
	global_load_dwordx4 v[156:159], v237, s[14:15] offset:512
	v_add_u32_e32 v236, v164, v234
	v_add_u32_e32 v237, v164, v235
	v_mov_b32_dpp v222, v56 row_ror:8 row_mask:0xf bank_mask:0xf
	v_mov_b32_dpp v223, v57 row_ror:8 row_mask:0xf bank_mask:0xf
	v_mov_b32_dpp v224, v58 row_ror:8 row_mask:0xf bank_mask:0xf
	v_mov_b32_dpp v225, v59 row_ror:8 row_mask:0xf bank_mask:0xf
	v_cndmask_b32_e32 v226, v222, v60, vcc
	v_cndmask_b32_e32 v227, v223, v61, vcc
	v_cndmask_b32_e32 v228, v224, v62, vcc
	v_cndmask_b32_e32 v229, v225, v63, vcc
	v_cndmask_b32_e32 v230, v60, v222, vcc
	v_cndmask_b32_e32 v231, v61, v223, vcc
	v_cndmask_b32_e32 v232, v62, v224, vcc
	v_cndmask_b32_e32 v233, v63, v225, vcc
	global_store_dwordx4 v236, v[226:229], s[72:73] sc1
	global_store_dwordx4 v237, v[230:233], s[72:73] sc1
	v_mov_b32_dpp v222, v44 row_ror:8 row_mask:0xf bank_mask:0xf
	v_mov_b32_dpp v223, v45 row_ror:8 row_mask:0xf bank_mask:0xf
	v_mov_b32_dpp v224, v46 row_ror:8 row_mask:0xf bank_mask:0xf
	v_mov_b32_dpp v225, v47 row_ror:8 row_mask:0xf bank_mask:0xf
	v_cndmask_b32_e32 v226, v222, v52, vcc
	v_cndmask_b32_e32 v227, v223, v53, vcc
	v_cndmask_b32_e32 v228, v224, v54, vcc
	v_cndmask_b32_e32 v229, v225, v55, vcc
	v_cndmask_b32_e32 v230, v52, v222, vcc
	v_cndmask_b32_e32 v231, v53, v223, vcc
	v_cndmask_b32_e32 v232, v54, v224, vcc
	v_cndmask_b32_e32 v233, v55, v225, vcc
	global_store_dwordx4 v236, v[226:229], s[72:73] offset:512 sc1
	global_store_dwordx4 v237, v[230:233], s[72:73] offset:512 sc1
	s_waitcnt vmcnt(20)
	v_mov_b32_dpp v222, v206 row_ror:8 row_mask:0xf bank_mask:0xf
	v_mov_b32_dpp v223, v207 row_ror:8 row_mask:0xf bank_mask:0xf
	v_mov_b32_dpp v224, v208 row_ror:8 row_mask:0xf bank_mask:0xf
	v_mov_b32_dpp v225, v209 row_ror:8 row_mask:0xf bank_mask:0xf
	v_mov_b32_dpp v226, v210 row_ror:8 row_mask:0xf bank_mask:0xf
	v_mov_b32_dpp v227, v211 row_ror:8 row_mask:0xf bank_mask:0xf
	v_mov_b32_dpp v228, v212 row_ror:8 row_mask:0xf bank_mask:0xf
	v_mov_b32_dpp v229, v213 row_ror:8 row_mask:0xf bank_mask:0xf
	v_cndmask_b32_e32 v230, v210, v206, vcc
	v_cndmask_b32_e32 v231, v211, v207, vcc
	v_cndmask_b32_e32 v232, v212, v208, vcc
	v_cndmask_b32_e32 v233, v213, v209, vcc
	v_cndmask_b32_e32 v222, v226, v222, vcc
	v_cndmask_b32_e32 v223, v227, v223, vcc
	v_cndmask_b32_e32 v224, v228, v224, vcc
	v_cndmask_b32_e32 v225, v229, v225, vcc
	v_pk_add_f32 v[48:49], v[230:231], v[48:49]
	v_pk_add_f32 v[50:51], v[232:233], v[50:51]
	v_pk_add_f32 v[40:41], v[222:223], v[40:41]
	v_pk_add_f32 v[42:43], v[224:225], v[42:43]
	v_mov_b32_dpp v222, v214 row_ror:8 row_mask:0xf bank_mask:0xf
	v_mov_b32_dpp v223, v215 row_ror:8 row_mask:0xf bank_mask:0xf
	v_mov_b32_dpp v224, v216 row_ror:8 row_mask:0xf bank_mask:0xf
	v_mov_b32_dpp v225, v217 row_ror:8 row_mask:0xf bank_mask:0xf
	v_mov_b32_dpp v226, v218 row_ror:8 row_mask:0xf bank_mask:0xf
	v_mov_b32_dpp v227, v219 row_ror:8 row_mask:0xf bank_mask:0xf
	v_mov_b32_dpp v228, v220 row_ror:8 row_mask:0xf bank_mask:0xf
	v_mov_b32_dpp v229, v221 row_ror:8 row_mask:0xf bank_mask:0xf
	v_cndmask_b32_e32 v230, v218, v214, vcc
	v_cndmask_b32_e32 v231, v219, v215, vcc
	v_cndmask_b32_e32 v232, v220, v216, vcc
	v_cndmask_b32_e32 v233, v221, v217, vcc
	v_cndmask_b32_e32 v222, v226, v222, vcc
	v_cndmask_b32_e32 v223, v227, v223, vcc
	v_cndmask_b32_e32 v224, v228, v224, vcc
	v_cndmask_b32_e32 v225, v229, v225, vcc
	v_pk_add_f32 v[36:37], v[230:231], v[36:37]
; __device__ __forceinline__ unsigned cvt_pk_bf16(float lo, float hi) { unsigned r; asm volatile("v_cvt_pk_bf16_f32 %0, %1, %2" : "=v"(r) : "v"(lo), "v"(hi)); return r; }
;     __device__ __forceinline__ void operator()(const f32x4 (&acc)[2][2][4][2], const Unit& u, int wr, int wc, int fr, int fq) const {
;     ...
;         for (int gi = 0; gi < 8; ++gi) {
;             const int ai = gi >> 2, m = gi & 3;
;             const int row = row0 + ai * HALF + m * 16;
;             const size_t off = (size_t)row * ldc + col0;
;             if (gi + 1 < 8) {
;                 const size_t offn = (size_t)(row0 + ((gi + 1) >> 2) * HALF + ((gi + 1) & 3) * 16) * ldc + col0;
; #pragma unroll
;                 for (int q = 0; q < 4; ++q) bs[(gi + 1) & 1][q] = *(const f32x4*)(xin + offn + (q >> 1) * HALF + (q & 1) * 16);
;             }
;             float sq = 0.f;
; #pragma unroll
;             for (int q = 0; q < 4; ++q) {
;                 const int bj = q >> 1, n = q & 1;
;                 const f32x4 o = bs[gi & 1][q] + acc[ai][bj][m][n];
;                 *(f32x4*)(out + off + bj * HALF + n * 16) = o;
;                 if (ss) {
;                     u32x2 w; w.x = cvt_pk_bf16(o[0], o[1]); w.y = cvt_pk_bf16(o[2], o[3]);
;                     *(u32x2*)(xb + off + bj * HALF + n * 16) = w;
;                     sq += (o[0] * o[0] + o[1] * o[1]) + (o[2] * o[2] + o[3] * o[3]);
;                 }
;             }
	v_pk_add_f32 v[38:39], v[232:233], v[38:39]
	v_pk_add_f32 v[28:29], v[222:223], v[28:29]
	v_pk_add_f32 v[30:31], v[224:225], v[30:31]
	v_add_u32_e32 v236, v165, v234
	v_add_u32_e32 v237, v165, v235
	v_mov_b32_dpp v222, v40 row_ror:8 row_mask:0xf bank_mask:0xf
	v_mov_b32_dpp v223, v41 row_ror:8 row_mask:0xf bank_mask:0xf
	v_mov_b32_dpp v224, v42 row_ror:8 row_mask:0xf bank_mask:0xf
	v_mov_b32_dpp v225, v43 row_ror:8 row_mask:0xf bank_mask:0xf
	v_cndmask_b32_e32 v226, v222, v48, vcc
	v_cndmask_b32_e32 v227, v223, v49, vcc
	v_cndmask_b32_e32 v228, v224, v50, vcc
	v_cndmask_b32_e32 v229, v225, v51, vcc
	v_cndmask_b32_e32 v230, v48, v222, vcc
	v_cndmask_b32_e32 v231, v49, v223, vcc
	v_cndmask_b32_e32 v232, v50, v224, vcc
	v_cndmask_b32_e32 v233, v51, v225, vcc
	global_store_dwordx4 v236, v[226:229], s[72:73] sc1
	global_store_dwordx4 v237, v[230:233], s[72:73] sc1
	v_mov_b32_dpp v222, v28 row_ror:8 row_mask:0xf bank_mask:0xf
	v_mov_b32_dpp v223, v29 row_ror:8 row_mask:0xf bank_mask:0xf
	v_mov_b32_dpp v224, v30 row_ror:8 row_mask:0xf bank_mask:0xf
	v_mov_b32_dpp v225, v31 row_ror:8 row_mask:0xf bank_mask:0xf
	v_cndmask_b32_e32 v226, v222, v36, vcc
	v_cndmask_b32_e32 v227, v223, v37, vcc
	v_cndmask_b32_e32 v228, v224, v38, vcc
	v_cndmask_b32_e32 v229, v225, v39, vcc
	v_cndmask_b32_e32 v230, v36, v222, vcc
	v_cndmask_b32_e32 v231, v37, v223, vcc
	v_cndmask_b32_e32 v232, v38, v224, vcc
	v_cndmask_b32_e32 v233, v39, v225, vcc
	global_store_dwordx4 v236, v[226:229], s[72:73] offset:512 sc1
	global_store_dwordx4 v237, v[230:233], s[72:73] offset:512 sc1
	s_waitcnt vmcnt(16)
	v_mov_b32_dpp v222, v128 row_ror:8 row_mask:0xf bank_mask:0xf
	v_mov_b32_dpp v223, v129 row_ror:8 row_mask:0xf bank_mask:0xf
	v_mov_b32_dpp v224, v130 row_ror:8 row_mask:0xf bank_mask:0xf
	v_mov_b32_dpp v225, v131 row_ror:8 row_mask:0xf bank_mask:0xf
	v_mov_b32_dpp v226, v132 row_ror:8 row_mask:0xf bank_mask:0xf
	v_mov_b32_dpp v227, v133 row_ror:8 row_mask:0xf bank_mask:0xf
	v_mov_b32_dpp v228, v134 row_ror:8 row_mask:0xf bank_mask:0xf
	v_mov_b32_dpp v229, v135 row_ror:8 row_mask:0xf bank_mask:0xf
	v_cndmask_b32_e32 v230, v132, v128, vcc
	v_cndmask_b32_e32 v231, v133, v129, vcc
	v_cndmask_b32_e32 v232, v134, v130, vcc
	v_cndmask_b32_e32 v233, v135, v131, vcc
	v_cndmask_b32_e32 v222, v226, v222, vcc
	v_cndmask_b32_e32 v223, v227, v223, vcc
	v_cndmask_b32_e32 v224, v228, v224, vcc
	v_cndmask_b32_e32 v225, v229, v225, vcc
	v_pk_add_f32 v[32:33], v[230:231], v[32:33]
	v_pk_add_f32 v[34:35], v[232:233], v[34:35]
	v_pk_add_f32 v[24:25], v[222:223], v[24:25]
	v_pk_add_f32 v[26:27], v[224:225], v[26:27]
	v_mov_b32_dpp v222, v136 row_ror:8 row_mask:0xf bank_mask:0xf
	v_mov_b32_dpp v223, v137 row_ror:8 row_mask:0xf bank_mask:0xf
	v_mov_b32_dpp v224, v138 row_ror:8 row_mask:0xf bank_mask:0xf
	v_mov_b32_dpp v225, v139 row_ror:8 row_mask:0xf bank_mask:0xf
	v_mov_b32_dpp v226, v140 row_ror:8 row_mask:0xf bank_mask:0xf
	v_mov_b32_dpp v227, v141 row_ror:8 row_mask:0xf bank_mask:0xf
	v_mov_b32_dpp v228, v142 row_ror:8 row_mask:0xf bank_mask:0xf
	v_mov_b32_dpp v229, v143 row_ror:8 row_mask:0xf bank_mask:0xf
	v_cndmask_b32_e32 v230, v140, v136, vcc
	v_cndmask_b32_e32 v231, v141, v137, vcc
	v_cndmask_b32_e32 v232, v142, v138, vcc
	v_cndmask_b32_e32 v233, v143, v139, vcc
	v_cndmask_b32_e32 v222, v226, v222, vcc
	v_cndmask_b32_e32 v223, v227, v223, vcc
	v_cndmask_b32_e32 v224, v228, v224, vcc
	v_cndmask_b32_e32 v225, v229, v225, vcc
	v_pk_add_f32 v[20:21], v[230:231], v[20:21]
	v_pk_add_f32 v[22:23], v[232:233], v[22:23]
	v_pk_add_f32 v[12:13], v[222:223], v[12:13]
	v_pk_add_f32 v[14:15], v[224:225], v[14:15]
	v_add_u32_e32 v236, v192, v234
	v_add_u32_e32 v237, v192, v235
	v_mov_b32_dpp v222, v24 row_ror:8 row_mask:0xf bank_mask:0xf
	v_mov_b32_dpp v223, v25 row_ror:8 row_mask:0xf bank_mask:0xf
	v_mov_b32_dpp v224, v26 row_ror:8 row_mask:0xf bank_mask:0xf
	v_mov_b32_dpp v225, v27 row_ror:8 row_mask:0xf bank_mask:0xf
	v_cndmask_b32_e32 v226, v222, v32, vcc
	v_cndmask_b32_e32 v227, v223, v33, vcc
	v_cndmask_b32_e32 v228, v224, v34, vcc
	v_cndmask_b32_e32 v229, v225, v35, vcc
	v_cndmask_b32_e32 v230, v32, v222, vcc
	v_cndmask_b32_e32 v231, v33, v223, vcc
	v_cndmask_b32_e32 v232, v34, v224, vcc
	v_cndmask_b32_e32 v233, v35, v225, vcc
	global_store_dwordx4 v236, v[226:229], s[72:73] sc1
	global_store_dwordx4 v237, v[230:233], s[72:73] sc1
	v_mov_b32_dpp v222, v12 row_ror:8 row_mask:0xf bank_mask:0xf
	v_mov_b32_dpp v223, v13 row_ror:8 row_mask:0xf bank_mask:0xf
	v_mov_b32_dpp v224, v14 row_ror:8 row_mask:0xf bank_mask:0xf
	v_mov_b32_dpp v225, v15 row_ror:8 row_mask:0xf bank_mask:0xf
	v_cndmask_b32_e32 v226, v222, v20, vcc
	v_cndmask_b32_e32 v227, v223, v21, vcc
	v_cndmask_b32_e32 v228, v224, v22, vcc
	v_cndmask_b32_e32 v229, v225, v23, vcc
	v_cndmask_b32_e32 v230, v20, v222, vcc
	v_cndmask_b32_e32 v231, v21, v223, vcc
	v_cndmask_b32_e32 v232, v22, v224, vcc
	v_cndmask_b32_e32 v233, v23, v225, vcc
	global_store_dwordx4 v236, v[226:229], s[72:73] offset:512 sc1
	global_store_dwordx4 v237, v[230:233], s[72:73] offset:512 sc1
	s_waitcnt vmcnt(12)
; __device__ __forceinline__ unsigned cvt_pk_bf16(float lo, float hi) { unsigned r; asm volatile("v_cvt_pk_bf16_f32 %0, %1, %2" : "=v"(r) : "v"(lo), "v"(hi)); return r; }
;     __device__ __forceinline__ void operator()(const f32x4 (&acc)[2][2][4][2], const Unit& u, int wr, int wc, int fr, int fq) const {
;     ...
;         for (int gi = 0; gi < 8; ++gi) {
;             const int ai = gi >> 2, m = gi & 3;
;             const int row = row0 + ai * HALF + m * 16;
;             const size_t off = (size_t)row * ldc + col0;
;             if (gi + 1 < 8) {
;                 const size_t offn = (size_t)(row0 + ((gi + 1) >> 2) * HALF + ((gi + 1) & 3) * 16) * ldc + col0;
; #pragma unroll
;                 for (int q = 0; q < 4; ++q) bs[(gi + 1) & 1][q] = *(const f32x4*)(xin + offn + (q >> 1) * HALF + (q & 1) * 16);
;             }
;             float sq = 0.f;
; #pragma unroll
;             for (int q = 0; q < 4; ++q) {
;                 const int bj = q >> 1, n = q & 1;
;                 const f32x4 o = bs[gi & 1][q] + acc[ai][bj][m][n];
;                 *(f32x4*)(out + off + bj * HALF + n * 16) = o;
;                 if (ss) {
;                     u32x2 w; w.x = cvt_pk_bf16(o[0], o[1]); w.y = cvt_pk_bf16(o[2], o[3]);
;                     *(u32x2*)(xb + off + bj * HALF + n * 16) = w;
;                     sq += (o[0] * o[0] + o[1] * o[1]) + (o[2] * o[2] + o[3] * o[3]);
;                 }
;             }
	v_mov_b32_dpp v222, v144 row_ror:8 row_mask:0xf bank_mask:0xf
	v_mov_b32_dpp v223, v145 row_ror:8 row_mask:0xf bank_mask:0xf
	v_mov_b32_dpp v224, v146 row_ror:8 row_mask:0xf bank_mask:0xf
	v_mov_b32_dpp v225, v147 row_ror:8 row_mask:0xf bank_mask:0xf
	v_mov_b32_dpp v226, v148 row_ror:8 row_mask:0xf bank_mask:0xf
	v_mov_b32_dpp v227, v149 row_ror:8 row_mask:0xf bank_mask:0xf
	v_mov_b32_dpp v228, v150 row_ror:8 row_mask:0xf bank_mask:0xf
	v_mov_b32_dpp v229, v151 row_ror:8 row_mask:0xf bank_mask:0xf
	v_cndmask_b32_e32 v230, v148, v144, vcc
	v_cndmask_b32_e32 v231, v149, v145, vcc
	v_cndmask_b32_e32 v232, v150, v146, vcc
	v_cndmask_b32_e32 v233, v151, v147, vcc
	v_cndmask_b32_e32 v222, v226, v222, vcc
	v_cndmask_b32_e32 v223, v227, v223, vcc
	v_cndmask_b32_e32 v224, v228, v224, vcc
	v_cndmask_b32_e32 v225, v229, v225, vcc
	v_pk_add_f32 v[16:17], v[230:231], v[16:17]
	v_pk_add_f32 v[18:19], v[232:233], v[18:19]
	v_pk_add_f32 v[8:9], v[222:223], v[8:9]
	v_pk_add_f32 v[10:11], v[224:225], v[10:11]
	v_mov_b32_dpp v222, v152 row_ror:8 row_mask:0xf bank_mask:0xf
	v_mov_b32_dpp v223, v153 row_ror:8 row_mask:0xf bank_mask:0xf
	v_mov_b32_dpp v224, v154 row_ror:8 row_mask:0xf bank_mask:0xf
	v_mov_b32_dpp v225, v155 row_ror:8 row_mask:0xf bank_mask:0xf
	v_mov_b32_dpp v226, v156 row_ror:8 row_mask:0xf bank_mask:0xf
	v_mov_b32_dpp v227, v157 row_ror:8 row_mask:0xf bank_mask:0xf
	v_mov_b32_dpp v228, v158 row_ror:8 row_mask:0xf bank_mask:0xf
	v_mov_b32_dpp v229, v159 row_ror:8 row_mask:0xf bank_mask:0xf
	v_cndmask_b32_e32 v230, v156, v152, vcc
	v_cndmask_b32_e32 v231, v157, v153, vcc
	v_cndmask_b32_e32 v232, v158, v154, vcc
	v_cndmask_b32_e32 v233, v159, v155, vcc
	v_cndmask_b32_e32 v222, v226, v222, vcc
	v_cndmask_b32_e32 v223, v227, v223, vcc
	v_cndmask_b32_e32 v224, v228, v224, vcc
	v_cndmask_b32_e32 v225, v229, v225, vcc
	v_pk_add_f32 v[4:5], v[230:231], v[4:5]
	v_pk_add_f32 v[6:7], v[232:233], v[6:7]
	v_pk_add_f32 v[0:1], v[222:223], v[0:1]
	v_pk_add_f32 v[2:3], v[224:225], v[2:3]
	v_add_u32_e32 v236, v193, v234
	v_add_u32_e32 v237, v193, v235
	v_mov_b32_dpp v222, v8 row_ror:8 row_mask:0xf bank_mask:0xf
	v_mov_b32_dpp v223, v9 row_ror:8 row_mask:0xf bank_mask:0xf
	v_mov_b32_dpp v224, v10 row_ror:8 row_mask:0xf bank_mask:0xf
	v_mov_b32_dpp v225, v11 row_ror:8 row_mask:0xf bank_mask:0xf
	v_cndmask_b32_e32 v226, v222, v16, vcc
	v_cndmask_b32_e32 v227, v223, v17, vcc
	v_cndmask_b32_e32 v228, v224, v18, vcc
	v_cndmask_b32_e32 v229, v225, v19, vcc
	v_cndmask_b32_e32 v230, v16, v222, vcc
	v_cndmask_b32_e32 v231, v17, v223, vcc
	v_cndmask_b32_e32 v232, v18, v224, vcc
	v_cndmask_b32_e32 v233, v19, v225, vcc
	global_store_dwordx4 v236, v[226:229], s[72:73] sc1
	global_store_dwordx4 v237, v[230:233], s[72:73] sc1
	v_mov_b32_dpp v222, v0 row_ror:8 row_mask:0xf bank_mask:0xf
	v_mov_b32_dpp v223, v1 row_ror:8 row_mask:0xf bank_mask:0xf
	v_mov_b32_dpp v224, v2 row_ror:8 row_mask:0xf bank_mask:0xf
	v_mov_b32_dpp v225, v3 row_ror:8 row_mask:0xf bank_mask:0xf
	v_cndmask_b32_e32 v226, v222, v4, vcc
	v_cndmask_b32_e32 v227, v223, v5, vcc
	v_cndmask_b32_e32 v228, v224, v6, vcc
	v_cndmask_b32_e32 v229, v225, v7, vcc
	v_cndmask_b32_e32 v230, v4, v222, vcc
	v_cndmask_b32_e32 v231, v5, v223, vcc
	v_cndmask_b32_e32 v232, v6, v224, vcc
	v_cndmask_b32_e32 v233, v7, v225, vcc
	global_store_dwordx4 v236, v[226:229], s[72:73] offset:512 sc1
	global_store_dwordx4 v237, v[230:233], s[72:73] offset:512 sc1

; __device__ __forceinline__ unsigned cvt_pk_bf16(float lo, float hi) { unsigned r; asm volatile("v_cvt_pk_bf16_f32 %0, %1, %2" : "=v"(r) : "v"(lo), "v"(hi)); return r; }
;     __device__ __forceinline__ void operator()(const f32x4 (&acc)[2][2][4][2], const Unit& u, int wr, int wc, int fr, int fq) const {
;     ...
;                 const int row = row0 + ai * HALF + m * 16;
;                 bf16_t* rowp = O + (size_t)row * ldc + col0;
;                 float ss = 0.f;
;                 const float rs = rsv[ai * 4 + m];
; #pragma unroll
;                 for (int bj = 0; bj < 2; ++bj) {
;                     f32x4 v0 = acc[ai][bj][m][0] * rs, v1 = acc[ai][bj][m][1] * rs;
;                     if (act == ACT_GELU_VSS) {
;                         f32x2 a = gelu_pk((f32x2){v0[0], v0[1]}), b = gelu_pk((f32x2){v0[2], v0[3]}), c = gelu_pk((f32x2){v1[0], v1[1]}), d = gelu_pk((f32x2){v1[2], v1[3]});
;                         v0 = (f32x4){a.x, a.y, b.x, b.y}; v1 = (f32x4){c.x, c.y, d.x, d.y};
;                         ss += (v0[0] * v0[0] + v0[1] * v0[1]) + (v0[2] * v0[2] + v0[3] * v0[3]) + (v1[0] * v1[0] + v1[1] * v1[1]) + (v1[2] * v1[2] + v1[3] * v1[3]);
;                     } else if (act == ACT_RELU2) {
; #pragma unroll
;                         for (int j = 0; j < 4; ++j) { const float a = fmaxf(v0[j], 0.f), b = fmaxf(v1[j], 0.f); v0[j] = a * a; v1[j] = b * b; }
;                     } else if (act == ACT_COLSCALE) {
;                         v0 = v0 * *(const f32x4*)(colscale + col0 + bj * HALF); v1 = v1 * *(const f32x4*)(colscale + col0 + bj * HALF + 4);
;                     }
;                     u32x4 w; w.x = cvt_pk_bf16(v0[0], v0[1]); w.y = cvt_pk_bf16(v0[2], v0[3]); w.z = cvt_pk_bf16(v1[0], v1[1]); w.w = cvt_pk_bf16(v1[2], v1[3]);
;                     *(u32x4*)(rowp + bj * HALF) = w;
.LBB0_447:
	v_mad_u64_u32 v[120:121], s[0:1], v180, s42, 0
	v_mov_b32_e32 v122, v121
	v_mad_u64_u32 v[122:123], s[0:1], v181, s42, v[122:123]
	v_mov_b32_e32 v121, v122
	v_lshl_add_u64 v[120:121], v[120:121], 1, s[20:21]
	v_lshl_add_u64 v[120:121], v[130:131], 1, v[120:121]
	v_cvt_pk_bf16_f32 v122, v134, v135
	v_cvt_pk_bf16_f32 v123, v132, v133
	v_cvt_pk_bf16_f32 v124, v140, v141
	v_cvt_pk_bf16_f32 v125, v138, v139
	global_store_dwordx4 v[120:121], v[122:125], off sc1
	v_mov_b32_e32 v195, v194
	v_pk_mul_f32 v[116:117], v[116:117], v[194:195]
	v_mov_b32_e32 v122, v194
	v_mov_b32_e32 v123, v194
	v_pk_mul_f32 v[118:119], v[118:119], v[122:123]
	v_pk_mul_f32 v[114:115], v[114:115], v[122:123]
	v_pk_mul_f32 v[112:113], v[112:113], v[194:195]
	s_cmp_lt_i32 s43, 2
	s_mov_b64 s[0:1], -1
	s_cbranch_scc1 .LBB0_453
	s_cmp_gt_i32 s43, 2
	s_cbranch_scc0 .LBB0_450
	v_lshl_add_u64 v[122:123], v[130:131], 2, s[96:97]
	global_load_dwordx4 v[124:127], v[122:123], off offset:512
	global_load_dwordx4 v[132:135], v[122:123], off offset:528
	s_mov_b64 s[0:1], 0
	s_waitcnt vmcnt(0)
	v_pk_mul_f32 v[122:123], v[118:119], v[126:127]
	v_pk_mul_f32 v[124:125], v[116:117], v[124:125]
	v_pk_mul_f32 v[126:127], v[114:115], v[134:135]
	v_pk_mul_f32 v[132:133], v[112:113], v[132:133]

; __device__ __forceinline__ unsigned cvt_pk_bf16(float lo, float hi) { unsigned r; asm volatile("v_cvt_pk_bf16_f32 %0, %1, %2" : "=v"(r) : "v"(lo), "v"(hi)); return r; }
;     __device__ __forceinline__ void operator()(const f32x4 (&acc)[2][2][4][2], const Unit& u, int wr, int wc, int fr, int fq) const {
;     ...
;                     u32x4 w; w.x = cvt_pk_bf16(v0[0], v0[1]); w.y = cvt_pk_bf16(v0[2], v0[3]); w.z = cvt_pk_bf16(v1[0], v1[1]); w.w = cvt_pk_bf16(v1[2], v1[3]);
;                     *(u32x4*)(rowp + bj * HALF) = w;
;                 }
;                 if (do_vss) { ss += __shfl_xor(ss, 16); ss += __shfl_xor(ss, 32); if (fq == 0) vss[(size_t)row * 32 + (u.pn - 8) * 4 + wc] = ss; }
.LBB0_457:
	s_lshl_b32 s0, s2, 2
	s_sub_i32 s36, s0, 32
	s_ashr_i32 s37, s36, 31
	s_cmp_gt_i32 s2, 7
	s_cselect_b64 s[0:1], -1, 0
	s_and_b64 s[38:39], s[12:13], s[0:1]
	v_cndmask_b32_e64 v116, 0, 1, s[38:39]
	v_cmp_ne_u32_e64 s[0:1], 1, v116
	s_andn2_b64 vcc, exec, s[38:39]
	v_cvt_pk_bf16_f32 v112, v124, v125
	v_cvt_pk_bf16_f32 v113, v122, v123
	v_cvt_pk_bf16_f32 v114, v132, v133
	v_cvt_pk_bf16_f32 v115, v126, v127
	global_store_dwordx4 v[120:121], v[112:115], off offset:256 sc1
	s_cbranch_vccnz .LBB0_461
	s_nop 0
	v_and_b32_e32 v113, 64, v167
	v_xor_b32_e32 v112, 16, v167
	v_add_u32_e32 v113, 64, v113
	v_cmp_lt_i32_e32 vcc, v112, v113
	v_xor_b32_e32 v114, 32, v167
	s_nop 0
	v_cndmask_b32_e32 v112, v167, v112, vcc
	v_lshlrev_b32_e32 v112, 2, v112
	ds_bpermute_b32 v112, v112, v129
	v_cmp_lt_i32_e32 vcc, v114, v113
	s_waitcnt lgkmcnt(0)
	v_add_f32_e32 v112, v129, v112
	v_cndmask_b32_e32 v113, v167, v114, vcc
	v_lshlrev_b32_e32 v113, 2, v113
	ds_bpermute_b32 v113, v113, v112
	s_and_saveexec_b64 s[38:39], s[4:5]
	s_cbranch_execz .LBB0_460
	v_lshlrev_b64 v[114:115], 7, v[180:181]
	v_lshl_add_u64 v[114:115], s[22:23], 0, v[114:115]
	v_lshl_add_u64 v[114:115], s[36:37], 2, v[114:115]
	s_lshl_b32 s2, s53, 2
	v_lshl_add_u64 v[114:115], v[114:115], 0, s[2:3]
	s_waitcnt lgkmcnt(0)
	v_add_f32_e32 v112, v112, v113
	global_store_dword v[114:115], v112, off

; __device__ __forceinline__ unsigned cvt_pk_bf16(float lo, float hi) { unsigned r; asm volatile("v_cvt_pk_bf16_f32 %0, %1, %2" : "=v"(r) : "v"(lo), "v"(hi)); return r; }
;     __device__ __forceinline__ void operator()(const f32x4 (&acc)[2][2][4][2], const Unit& u, int wr, int wc, int fr, int fq) const {
;     ...
;                 const int row = row0 + ai * HALF + m * 16;
;                 bf16_t* rowp = O + (size_t)row * ldc + col0;
;                 float ss = 0.f;
;                 const float rs = rsv[ai * 4 + m];
; #pragma unroll
;                 for (int bj = 0; bj < 2; ++bj) {
;                     f32x4 v0 = acc[ai][bj][m][0] * rs, v1 = acc[ai][bj][m][1] * rs;
;                     if (act == ACT_GELU_VSS) {
;                         f32x2 a = gelu_pk((f32x2){v0[0], v0[1]}), b = gelu_pk((f32x2){v0[2], v0[3]}), c = gelu_pk((f32x2){v1[0], v1[1]}), d = gelu_pk((f32x2){v1[2], v1[3]});
;                         v0 = (f32x4){a.x, a.y, b.x, b.y}; v1 = (f32x4){c.x, c.y, d.x, d.y};
;                         ss += (v0[0] * v0[0] + v0[1] * v0[1]) + (v0[2] * v0[2] + v0[3] * v0[3]) + (v1[0] * v1[0] + v1[1] * v1[1]) + (v1[2] * v1[2] + v1[3] * v1[3]);
;                     } else if (act == ACT_RELU2) {
; #pragma unroll
;                         for (int j = 0; j < 4; ++j) { const float a = fmaxf(v0[j], 0.f), b = fmaxf(v1[j], 0.f); v0[j] = a * a; v1[j] = b * b; }
;                     } else if (act == ACT_COLSCALE) {
;                         v0 = v0 * *(const f32x4*)(colscale + col0 + bj * HALF); v1 = v1 * *(const f32x4*)(colscale + col0 + bj * HALF + 4);
;                     }
;                     u32x4 w; w.x = cvt_pk_bf16(v0[0], v0[1]); w.y = cvt_pk_bf16(v0[2], v0[3]); w.z = cvt_pk_bf16(v1[0], v1[1]); w.w = cvt_pk_bf16(v1[2], v1[3]);
;                     *(u32x4*)(rowp + bj * HALF) = w;
.LBB0_471:
	v_mad_u64_u32 v[104:105], s[38:39], v188, s42, 0
	v_mov_b32_e32 v106, v105
	v_mad_u64_u32 v[106:107], s[38:39], v189, s42, v[106:107]
	v_mov_b32_e32 v105, v106
	v_lshl_add_u64 v[104:105], v[104:105], 1, s[20:21]
	v_lshl_add_u64 v[104:105], v[130:131], 1, v[104:105]
	v_cvt_pk_bf16_f32 v106, v114, v115
	s_waitcnt lgkmcnt(0)
	v_cvt_pk_bf16_f32 v107, v112, v113
	v_cvt_pk_bf16_f32 v108, v118, v119
	v_cvt_pk_bf16_f32 v109, v116, v117
	global_store_dwordx4 v[104:105], v[106:109], off sc1
	v_mov_b32_e32 v193, v192
	v_pk_mul_f32 v[100:101], v[100:101], v[192:193]
	v_mov_b32_e32 v106, v192
	v_mov_b32_e32 v107, v192
	v_pk_mul_f32 v[102:103], v[102:103], v[106:107]
	v_pk_mul_f32 v[98:99], v[98:99], v[106:107]
	v_pk_mul_f32 v[96:97], v[96:97], v[192:193]
	s_cmp_lt_i32 s43, 2
	s_mov_b64 s[38:39], -1
	s_cbranch_scc1 .LBB0_477
	s_cmp_gt_i32 s43, 2
	s_cbranch_scc0 .LBB0_474
	v_lshl_add_u64 v[106:107], v[130:131], 2, s[96:97]
	global_load_dwordx4 v[108:111], v[106:107], off offset:512
	global_load_dwordx4 v[112:115], v[106:107], off offset:528
	s_mov_b64 s[38:39], 0
	s_waitcnt vmcnt(0)
	v_pk_mul_f32 v[106:107], v[102:103], v[110:111]
	v_pk_mul_f32 v[108:109], v[100:101], v[108:109]
	v_pk_mul_f32 v[110:111], v[98:99], v[114:115]
	v_pk_mul_f32 v[112:113], v[96:97], v[112:113]

; __device__ __forceinline__ unsigned cvt_pk_bf16(float lo, float hi) { unsigned r; asm volatile("v_cvt_pk_bf16_f32 %0, %1, %2" : "=v"(r) : "v"(lo), "v"(hi)); return r; }
;     __device__ __forceinline__ void operator()(const f32x4 (&acc)[2][2][4][2], const Unit& u, int wr, int wc, int fr, int fq) const {
;     ...
;                     u32x4 w; w.x = cvt_pk_bf16(v0[0], v0[1]); w.y = cvt_pk_bf16(v0[2], v0[3]); w.z = cvt_pk_bf16(v1[0], v1[1]); w.w = cvt_pk_bf16(v1[2], v1[3]);
;                     *(u32x4*)(rowp + bj * HALF) = w;
;                 }
;                 if (do_vss) { ss += __shfl_xor(ss, 16); ss += __shfl_xor(ss, 32); if (fq == 0) vss[(size_t)row * 32 + (u.pn - 8) * 4 + wc] = ss; }
.LBB0_481:
	s_and_b64 vcc, exec, s[0:1]
	v_cvt_pk_bf16_f32 v96, v108, v109
	v_cvt_pk_bf16_f32 v97, v106, v107
	v_cvt_pk_bf16_f32 v98, v112, v113
	v_cvt_pk_bf16_f32 v99, v110, v111
	global_store_dwordx4 v[104:105], v[96:99], off offset:256 sc1
	s_cbranch_vccnz .LBB0_485
	s_nop 0
	v_and_b32_e32 v97, 64, v167
	v_xor_b32_e32 v96, 16, v167
	v_add_u32_e32 v97, 64, v97
	v_cmp_lt_i32_e32 vcc, v96, v97
	v_xor_b32_e32 v98, 32, v167
	s_nop 0
	v_cndmask_b32_e32 v96, v167, v96, vcc
	v_lshlrev_b32_e32 v96, 2, v96
	ds_bpermute_b32 v96, v96, v120
	v_cmp_lt_i32_e32 vcc, v98, v97
	s_waitcnt lgkmcnt(0)
	v_add_f32_e32 v96, v120, v96
	v_cndmask_b32_e32 v97, v167, v98, vcc
	v_lshlrev_b32_e32 v97, 2, v97
	ds_bpermute_b32 v97, v97, v96
	s_and_saveexec_b64 s[38:39], s[4:5]
	s_cbranch_execz .LBB0_484
	v_lshlrev_b64 v[98:99], 7, v[188:189]
	v_lshl_add_u64 v[98:99], s[22:23], 0, v[98:99]
	v_lshl_add_u64 v[98:99], s[36:37], 2, v[98:99]
	s_lshl_b32 s2, s53, 2
	v_lshl_add_u64 v[98:99], v[98:99], 0, s[2:3]
	s_waitcnt lgkmcnt(0)
	v_add_f32_e32 v96, v96, v97
	global_store_dword v[98:99], v96, off

; __device__ __forceinline__ unsigned cvt_pk_bf16(float lo, float hi) { unsigned r; asm volatile("v_cvt_pk_bf16_f32 %0, %1, %2" : "=v"(r) : "v"(lo), "v"(hi)); return r; }
;     __device__ __forceinline__ void operator()(const f32x4 (&acc)[2][2][4][2], const Unit& u, int wr, int wc, int fr, int fq) const {
;     ...
;                 const int row = row0 + ai * HALF + m * 16;
;                 bf16_t* rowp = O + (size_t)row * ldc + col0;
;                 float ss = 0.f;
;                 const float rs = rsv[ai * 4 + m];
; #pragma unroll
;                 for (int bj = 0; bj < 2; ++bj) {
;                     f32x4 v0 = acc[ai][bj][m][0] * rs, v1 = acc[ai][bj][m][1] * rs;
;                     if (act == ACT_GELU_VSS) {
;                         f32x2 a = gelu_pk((f32x2){v0[0], v0[1]}), b = gelu_pk((f32x2){v0[2], v0[3]}), c = gelu_pk((f32x2){v1[0], v1[1]}), d = gelu_pk((f32x2){v1[2], v1[3]});
;                         v0 = (f32x4){a.x, a.y, b.x, b.y}; v1 = (f32x4){c.x, c.y, d.x, d.y};
;                         ss += (v0[0] * v0[0] + v0[1] * v0[1]) + (v0[2] * v0[2] + v0[3] * v0[3]) + (v1[0] * v1[0] + v1[1] * v1[1]) + (v1[2] * v1[2] + v1[3] * v1[3]);
;                     } else if (act == ACT_RELU2) {
; #pragma unroll
;                         for (int j = 0; j < 4; ++j) { const float a = fmaxf(v0[j], 0.f), b = fmaxf(v1[j], 0.f); v0[j] = a * a; v1[j] = b * b; }
;                     } else if (act == ACT_COLSCALE) {
;                         v0 = v0 * *(const f32x4*)(colscale + col0 + bj * HALF); v1 = v1 * *(const f32x4*)(colscale + col0 + bj * HALF + 4);
;                     }
;                     u32x4 w; w.x = cvt_pk_bf16(v0[0], v0[1]); w.y = cvt_pk_bf16(v0[2], v0[3]); w.z = cvt_pk_bf16(v1[0], v1[1]); w.w = cvt_pk_bf16(v1[2], v1[3]);
;                     *(u32x4*)(rowp + bj * HALF) = w;
.LBB0_495:
	v_mad_u64_u32 v[88:89], s[38:39], v184, s42, 0
	v_mov_b32_e32 v90, v89
	v_mad_u64_u32 v[90:91], s[38:39], v185, s42, v[90:91]
	v_mov_b32_e32 v89, v90
	v_lshl_add_u64 v[88:89], v[88:89], 1, s[20:21]
	v_lshl_add_u64 v[88:89], v[130:131], 1, v[88:89]
	v_cvt_pk_bf16_f32 v90, v98, v99
	s_waitcnt lgkmcnt(0)
	v_cvt_pk_bf16_f32 v91, v96, v97
	v_cvt_pk_bf16_f32 v92, v102, v103
	v_cvt_pk_bf16_f32 v93, v100, v101
	global_store_dwordx4 v[88:89], v[90:93], off sc1
	v_mov_b32_e32 v191, v190
	v_pk_mul_f32 v[84:85], v[84:85], v[190:191]
	v_mov_b32_e32 v90, v190
	v_mov_b32_e32 v91, v190
	v_pk_mul_f32 v[86:87], v[86:87], v[90:91]
	v_pk_mul_f32 v[82:83], v[82:83], v[90:91]
	v_pk_mul_f32 v[80:81], v[80:81], v[190:191]
	s_cmp_lt_i32 s43, 2
	s_mov_b64 s[38:39], -1
	s_cbranch_scc1 .LBB0_501
	s_cmp_gt_i32 s43, 2
	s_cbranch_scc0 .LBB0_498
	v_lshl_add_u64 v[90:91], v[130:131], 2, s[96:97]
	global_load_dwordx4 v[92:95], v[90:91], off offset:512
	global_load_dwordx4 v[96:99], v[90:91], off offset:528
	s_mov_b64 s[38:39], 0
	s_waitcnt vmcnt(0)
	v_pk_mul_f32 v[90:91], v[86:87], v[94:95]
	v_pk_mul_f32 v[92:93], v[84:85], v[92:93]
	v_pk_mul_f32 v[94:95], v[82:83], v[98:99]
	v_pk_mul_f32 v[96:97], v[80:81], v[96:97]

; __device__ __forceinline__ unsigned cvt_pk_bf16(float lo, float hi) { unsigned r; asm volatile("v_cvt_pk_bf16_f32 %0, %1, %2" : "=v"(r) : "v"(lo), "v"(hi)); return r; }
;     __device__ __forceinline__ void operator()(const f32x4 (&acc)[2][2][4][2], const Unit& u, int wr, int wc, int fr, int fq) const {
;     ...
;                     u32x4 w; w.x = cvt_pk_bf16(v0[0], v0[1]); w.y = cvt_pk_bf16(v0[2], v0[3]); w.z = cvt_pk_bf16(v1[0], v1[1]); w.w = cvt_pk_bf16(v1[2], v1[3]);
;                     *(u32x4*)(rowp + bj * HALF) = w;
;                 }
;                 if (do_vss) { ss += __shfl_xor(ss, 16); ss += __shfl_xor(ss, 32); if (fq == 0) vss[(size_t)row * 32 + (u.pn - 8) * 4 + wc] = ss; }
.LBB0_505:
	s_and_b64 vcc, exec, s[0:1]
	v_cvt_pk_bf16_f32 v80, v92, v93
	v_cvt_pk_bf16_f32 v81, v90, v91
	v_cvt_pk_bf16_f32 v82, v96, v97
	v_cvt_pk_bf16_f32 v83, v94, v95
	global_store_dwordx4 v[88:89], v[80:83], off offset:256 sc1
	s_cbranch_vccnz .LBB0_509
	s_nop 0
	v_and_b32_e32 v81, 64, v167
	v_xor_b32_e32 v80, 16, v167
	v_add_u32_e32 v81, 64, v81
	v_cmp_lt_i32_e32 vcc, v80, v81
	v_xor_b32_e32 v82, 32, v167
	s_nop 0
	v_cndmask_b32_e32 v80, v167, v80, vcc
	v_lshlrev_b32_e32 v80, 2, v80
	ds_bpermute_b32 v80, v80, v104
	v_cmp_lt_i32_e32 vcc, v82, v81
	s_waitcnt lgkmcnt(0)
	v_add_f32_e32 v80, v104, v80
	v_cndmask_b32_e32 v81, v167, v82, vcc
	v_lshlrev_b32_e32 v81, 2, v81
	ds_bpermute_b32 v81, v81, v80
	s_and_saveexec_b64 s[38:39], s[4:5]
	s_cbranch_execz .LBB0_508
	v_lshlrev_b64 v[82:83], 7, v[184:185]
	v_lshl_add_u64 v[82:83], s[22:23], 0, v[82:83]
	v_lshl_add_u64 v[82:83], s[36:37], 2, v[82:83]
	s_lshl_b32 s2, s53, 2
	v_lshl_add_u64 v[82:83], v[82:83], 0, s[2:3]
	s_waitcnt lgkmcnt(0)
	v_add_f32_e32 v80, v80, v81
	global_store_dword v[82:83], v80, off

; __device__ __forceinline__ unsigned cvt_pk_bf16(float lo, float hi) { unsigned r; asm volatile("v_cvt_pk_bf16_f32 %0, %1, %2" : "=v"(r) : "v"(lo), "v"(hi)); return r; }
;     __device__ __forceinline__ void operator()(const f32x4 (&acc)[2][2][4][2], const Unit& u, int wr, int wc, int fr, int fq) const {
;     ...
;                 const int row = row0 + ai * HALF + m * 16;
;                 bf16_t* rowp = O + (size_t)row * ldc + col0;
;                 float ss = 0.f;
;                 const float rs = rsv[ai * 4 + m];
; #pragma unroll
;                 for (int bj = 0; bj < 2; ++bj) {
;                     f32x4 v0 = acc[ai][bj][m][0] * rs, v1 = acc[ai][bj][m][1] * rs;
;                     if (act == ACT_GELU_VSS) {
;                         f32x2 a = gelu_pk((f32x2){v0[0], v0[1]}), b = gelu_pk((f32x2){v0[2], v0[3]}), c = gelu_pk((f32x2){v1[0], v1[1]}), d = gelu_pk((f32x2){v1[2], v1[3]});
;                         v0 = (f32x4){a.x, a.y, b.x, b.y}; v1 = (f32x4){c.x, c.y, d.x, d.y};
;                         ss += (v0[0] * v0[0] + v0[1] * v0[1]) + (v0[2] * v0[2] + v0[3] * v0[3]) + (v1[0] * v1[0] + v1[1] * v1[1]) + (v1[2] * v1[2] + v1[3] * v1[3]);
;                     } else if (act == ACT_RELU2) {
; #pragma unroll
;                         for (int j = 0; j < 4; ++j) { const float a = fmaxf(v0[j], 0.f), b = fmaxf(v1[j], 0.f); v0[j] = a * a; v1[j] = b * b; }
;                     } else if (act == ACT_COLSCALE) {
;                         v0 = v0 * *(const f32x4*)(colscale + col0 + bj * HALF); v1 = v1 * *(const f32x4*)(colscale + col0 + bj * HALF + 4);
;                     }
;                     u32x4 w; w.x = cvt_pk_bf16(v0[0], v0[1]); w.y = cvt_pk_bf16(v0[2], v0[3]); w.z = cvt_pk_bf16(v1[0], v1[1]); w.w = cvt_pk_bf16(v1[2], v1[3]);
;                     *(u32x4*)(rowp + bj * HALF) = w;
.LBB0_519:
	v_mad_u64_u32 v[72:73], s[38:39], v182, s42, 0
	v_mov_b32_e32 v74, v73
	v_mad_u64_u32 v[74:75], s[38:39], v183, s42, v[74:75]
	v_mov_b32_e32 v73, v74
	v_lshl_add_u64 v[72:73], v[72:73], 1, s[20:21]
	v_lshl_add_u64 v[72:73], v[130:131], 1, v[72:73]
	v_cvt_pk_bf16_f32 v74, v82, v83
	s_waitcnt lgkmcnt(0)
	v_cvt_pk_bf16_f32 v75, v80, v81
	v_cvt_pk_bf16_f32 v76, v86, v87
	v_cvt_pk_bf16_f32 v77, v84, v85
	global_store_dwordx4 v[72:73], v[74:77], off sc1
	v_mov_b32_e32 v187, v186
	v_pk_mul_f32 v[68:69], v[68:69], v[186:187]
	v_mov_b32_e32 v74, v186
	v_mov_b32_e32 v75, v186
	v_pk_mul_f32 v[70:71], v[70:71], v[74:75]
	v_pk_mul_f32 v[66:67], v[66:67], v[74:75]
	v_pk_mul_f32 v[64:65], v[64:65], v[186:187]
	s_cmp_lt_i32 s43, 2
	s_mov_b64 s[38:39], -1
	s_cbranch_scc1 .LBB0_525
	s_cmp_gt_i32 s43, 2
	s_cbranch_scc0 .LBB0_522
	v_lshl_add_u64 v[74:75], v[130:131], 2, s[96:97]
	global_load_dwordx4 v[76:79], v[74:75], off offset:512
	global_load_dwordx4 v[80:83], v[74:75], off offset:528
	s_mov_b64 s[38:39], 0
	s_waitcnt vmcnt(0)
	v_pk_mul_f32 v[74:75], v[70:71], v[78:79]
	v_pk_mul_f32 v[76:77], v[68:69], v[76:77]
	v_pk_mul_f32 v[78:79], v[66:67], v[82:83]
	v_pk_mul_f32 v[80:81], v[64:65], v[80:81]

; __device__ __forceinline__ unsigned cvt_pk_bf16(float lo, float hi) { unsigned r; asm volatile("v_cvt_pk_bf16_f32 %0, %1, %2" : "=v"(r) : "v"(lo), "v"(hi)); return r; }
;     __device__ __forceinline__ void operator()(const f32x4 (&acc)[2][2][4][2], const Unit& u, int wr, int wc, int fr, int fq) const {
;     ...
;                     u32x4 w; w.x = cvt_pk_bf16(v0[0], v0[1]); w.y = cvt_pk_bf16(v0[2], v0[3]); w.z = cvt_pk_bf16(v1[0], v1[1]); w.w = cvt_pk_bf16(v1[2], v1[3]);
;                     *(u32x4*)(rowp + bj * HALF) = w;
;                 }
;                 if (do_vss) { ss += __shfl_xor(ss, 16); ss += __shfl_xor(ss, 32); if (fq == 0) vss[(size_t)row * 32 + (u.pn - 8) * 4 + wc] = ss; }
.LBB0_529:
	s_and_b64 vcc, exec, s[0:1]
	v_cvt_pk_bf16_f32 v64, v76, v77
	v_cvt_pk_bf16_f32 v65, v74, v75
	v_cvt_pk_bf16_f32 v66, v80, v81
	v_cvt_pk_bf16_f32 v67, v78, v79
	global_store_dwordx4 v[72:73], v[64:67], off offset:256 sc1
	s_cbranch_vccnz .LBB0_533
	s_nop 0
	v_and_b32_e32 v65, 64, v167
	v_xor_b32_e32 v64, 16, v167
	v_add_u32_e32 v65, 64, v65
	v_cmp_lt_i32_e32 vcc, v64, v65
	v_xor_b32_e32 v66, 32, v167
	s_nop 0
	v_cndmask_b32_e32 v64, v167, v64, vcc
	v_lshlrev_b32_e32 v64, 2, v64
	ds_bpermute_b32 v64, v64, v88
	v_cmp_lt_i32_e32 vcc, v66, v65
	s_waitcnt lgkmcnt(0)
	v_add_f32_e32 v64, v88, v64
	v_cndmask_b32_e32 v65, v167, v66, vcc
	v_lshlrev_b32_e32 v65, 2, v65
	ds_bpermute_b32 v65, v65, v64
	s_and_saveexec_b64 s[38:39], s[4:5]
	s_cbranch_execz .LBB0_532
	v_lshlrev_b64 v[66:67], 7, v[182:183]
	v_lshl_add_u64 v[66:67], s[22:23], 0, v[66:67]
	v_lshl_add_u64 v[66:67], s[36:37], 2, v[66:67]
	s_lshl_b32 s2, s53, 2
	v_lshl_add_u64 v[66:67], v[66:67], 0, s[2:3]
	s_waitcnt lgkmcnt(0)
	v_add_f32_e32 v64, v64, v65
	global_store_dword v[66:67], v64, off

; __device__ __forceinline__ unsigned cvt_pk_bf16(float lo, float hi) { unsigned r; asm volatile("v_cvt_pk_bf16_f32 %0, %1, %2" : "=v"(r) : "v"(lo), "v"(hi)); return r; }
;     __device__ __forceinline__ void operator()(const f32x4 (&acc)[2][2][4][2], const Unit& u, int wr, int wc, int fr, int fq) const {
;     ...
;                 const int row = row0 + ai * HALF + m * 16;
;                 bf16_t* rowp = O + (size_t)row * ldc + col0;
;                 float ss = 0.f;
;                 const float rs = rsv[ai * 4 + m];
; #pragma unroll
;                 for (int bj = 0; bj < 2; ++bj) {
;                     f32x4 v0 = acc[ai][bj][m][0] * rs, v1 = acc[ai][bj][m][1] * rs;
;                     if (act == ACT_GELU_VSS) {
;                         f32x2 a = gelu_pk((f32x2){v0[0], v0[1]}), b = gelu_pk((f32x2){v0[2], v0[3]}), c = gelu_pk((f32x2){v1[0], v1[1]}), d = gelu_pk((f32x2){v1[2], v1[3]});
;                         v0 = (f32x4){a.x, a.y, b.x, b.y}; v1 = (f32x4){c.x, c.y, d.x, d.y};
;                         ss += (v0[0] * v0[0] + v0[1] * v0[1]) + (v0[2] * v0[2] + v0[3] * v0[3]) + (v1[0] * v1[0] + v1[1] * v1[1]) + (v1[2] * v1[2] + v1[3] * v1[3]);
;                     } else if (act == ACT_RELU2) {
; #pragma unroll
;                         for (int j = 0; j < 4; ++j) { const float a = fmaxf(v0[j], 0.f), b = fmaxf(v1[j], 0.f); v0[j] = a * a; v1[j] = b * b; }
;                     } else if (act == ACT_COLSCALE) {
;                         v0 = v0 * *(const f32x4*)(colscale + col0 + bj * HALF); v1 = v1 * *(const f32x4*)(colscale + col0 + bj * HALF + 4);
;                     }
;                     u32x4 w; w.x = cvt_pk_bf16(v0[0], v0[1]); w.y = cvt_pk_bf16(v0[2], v0[3]); w.z = cvt_pk_bf16(v1[0], v1[1]); w.w = cvt_pk_bf16(v1[2], v1[3]);
;                     *(u32x4*)(rowp + bj * HALF) = w;
.LBB0_543:
	v_add_u32_e32 v56, 0x80, v180
	v_mad_u64_u32 v[58:59], s[38:39], v56, s42, 0
	v_ashrrev_i32_e32 v57, 31, v56
	v_mov_b32_e32 v60, v59
	v_mad_u64_u32 v[60:61], s[38:39], v57, s42, v[60:61]
	v_mov_b32_e32 v59, v60
	v_lshl_add_u64 v[58:59], v[58:59], 1, s[20:21]
	v_lshl_add_u64 v[58:59], v[130:131], 1, v[58:59]
	v_cvt_pk_bf16_f32 v60, v66, v67
	s_waitcnt lgkmcnt(0)
	v_cvt_pk_bf16_f32 v61, v64, v65
	v_cvt_pk_bf16_f32 v62, v70, v71
	v_cvt_pk_bf16_f32 v63, v68, v69
	global_store_dwordx4 v[58:59], v[60:63], off sc1
	v_mov_b32_e32 v147, v146
	v_pk_mul_f32 v[52:53], v[52:53], v[146:147]
	v_mov_b32_e32 v60, v146
	v_mov_b32_e32 v61, v146
	v_pk_mul_f32 v[54:55], v[54:55], v[60:61]
	v_pk_mul_f32 v[50:51], v[50:51], v[60:61]
	v_pk_mul_f32 v[48:49], v[48:49], v[146:147]
	s_cmp_lt_i32 s43, 2
	s_mov_b64 s[38:39], -1
	s_cbranch_scc1 .LBB0_549
	s_cmp_gt_i32 s43, 2
	s_cbranch_scc0 .LBB0_546
	v_lshl_add_u64 v[60:61], v[130:131], 2, s[96:97]
	global_load_dwordx4 v[62:65], v[60:61], off offset:512
	global_load_dwordx4 v[66:69], v[60:61], off offset:528
	s_mov_b64 s[38:39], 0
	s_waitcnt vmcnt(0)
	v_pk_mul_f32 v[60:61], v[54:55], v[64:65]
	v_pk_mul_f32 v[62:63], v[52:53], v[62:63]
	v_pk_mul_f32 v[64:65], v[50:51], v[68:69]
	v_pk_mul_f32 v[66:67], v[48:49], v[66:67]

; __device__ __forceinline__ unsigned cvt_pk_bf16(float lo, float hi) { unsigned r; asm volatile("v_cvt_pk_bf16_f32 %0, %1, %2" : "=v"(r) : "v"(lo), "v"(hi)); return r; }
;     __device__ __forceinline__ void operator()(const f32x4 (&acc)[2][2][4][2], const Unit& u, int wr, int wc, int fr, int fq) const {
;     ...
;                     u32x4 w; w.x = cvt_pk_bf16(v0[0], v0[1]); w.y = cvt_pk_bf16(v0[2], v0[3]); w.z = cvt_pk_bf16(v1[0], v1[1]); w.w = cvt_pk_bf16(v1[2], v1[3]);
;                     *(u32x4*)(rowp + bj * HALF) = w;
;                 }
;                 if (do_vss) { ss += __shfl_xor(ss, 16); ss += __shfl_xor(ss, 32); if (fq == 0) vss[(size_t)row * 32 + (u.pn - 8) * 4 + wc] = ss; }
.LBB0_553:
	s_and_b64 vcc, exec, s[0:1]
	v_cvt_pk_bf16_f32 v48, v62, v63
	v_cvt_pk_bf16_f32 v49, v60, v61
	v_cvt_pk_bf16_f32 v50, v66, v67
	v_cvt_pk_bf16_f32 v51, v64, v65
	global_store_dwordx4 v[58:59], v[48:51], off offset:256 sc1
	s_cbranch_vccnz .LBB0_557
	s_nop 0
	v_and_b32_e32 v49, 64, v167
	v_xor_b32_e32 v48, 16, v167
	v_add_u32_e32 v49, 64, v49
	v_cmp_lt_i32_e32 vcc, v48, v49
	v_xor_b32_e32 v50, 32, v167
	s_nop 0
	v_cndmask_b32_e32 v48, v167, v48, vcc
	v_lshlrev_b32_e32 v48, 2, v48
	ds_bpermute_b32 v48, v48, v72
	v_cmp_lt_i32_e32 vcc, v50, v49
	s_waitcnt lgkmcnt(0)
	v_add_f32_e32 v48, v72, v48
	v_cndmask_b32_e32 v49, v167, v50, vcc
	v_lshlrev_b32_e32 v49, 2, v49
	ds_bpermute_b32 v49, v49, v48
	s_and_saveexec_b64 s[38:39], s[4:5]
	s_cbranch_execz .LBB0_556
	v_lshlrev_b64 v[50:51], 7, v[56:57]
	v_lshl_add_u64 v[50:51], s[22:23], 0, v[50:51]
	v_lshl_add_u64 v[50:51], s[36:37], 2, v[50:51]
	s_lshl_b32 s2, s53, 2
	v_lshl_add_u64 v[50:51], v[50:51], 0, s[2:3]
	s_waitcnt lgkmcnt(0)
	v_add_f32_e32 v48, v48, v49
	global_store_dword v[50:51], v48, off

; __device__ __forceinline__ unsigned cvt_pk_bf16(float lo, float hi) { unsigned r; asm volatile("v_cvt_pk_bf16_f32 %0, %1, %2" : "=v"(r) : "v"(lo), "v"(hi)); return r; }
;     __device__ __forceinline__ void operator()(const f32x4 (&acc)[2][2][4][2], const Unit& u, int wr, int wc, int fr, int fq) const {
;     ...
;                 const int row = row0 + ai * HALF + m * 16;
;                 bf16_t* rowp = O + (size_t)row * ldc + col0;
;                 float ss = 0.f;
;                 const float rs = rsv[ai * 4 + m];
; #pragma unroll
;                 for (int bj = 0; bj < 2; ++bj) {
;                     f32x4 v0 = acc[ai][bj][m][0] * rs, v1 = acc[ai][bj][m][1] * rs;
;                     if (act == ACT_GELU_VSS) {
;                         f32x2 a = gelu_pk((f32x2){v0[0], v0[1]}), b = gelu_pk((f32x2){v0[2], v0[3]}), c = gelu_pk((f32x2){v1[0], v1[1]}), d = gelu_pk((f32x2){v1[2], v1[3]});
;                         v0 = (f32x4){a.x, a.y, b.x, b.y}; v1 = (f32x4){c.x, c.y, d.x, d.y};
;                         ss += (v0[0] * v0[0] + v0[1] * v0[1]) + (v0[2] * v0[2] + v0[3] * v0[3]) + (v1[0] * v1[0] + v1[1] * v1[1]) + (v1[2] * v1[2] + v1[3] * v1[3]);
;                     } else if (act == ACT_RELU2) {
; #pragma unroll
;                         for (int j = 0; j < 4; ++j) { const float a = fmaxf(v0[j], 0.f), b = fmaxf(v1[j], 0.f); v0[j] = a * a; v1[j] = b * b; }
;                     } else if (act == ACT_COLSCALE) {
;                         v0 = v0 * *(const f32x4*)(colscale + col0 + bj * HALF); v1 = v1 * *(const f32x4*)(colscale + col0 + bj * HALF + 4);
;                     }
;                     u32x4 w; w.x = cvt_pk_bf16(v0[0], v0[1]); w.y = cvt_pk_bf16(v0[2], v0[3]); w.z = cvt_pk_bf16(v1[0], v1[1]); w.w = cvt_pk_bf16(v1[2], v1[3]);
;                     *(u32x4*)(rowp + bj * HALF) = w;
.LBB0_567:
	v_add_u32_e32 v40, 0x90, v180
	v_mad_u64_u32 v[42:43], s[38:39], v40, s42, 0
	v_ashrrev_i32_e32 v41, 31, v40
	v_mov_b32_e32 v44, v43
	v_mad_u64_u32 v[44:45], s[38:39], v41, s42, v[44:45]
	v_mov_b32_e32 v43, v44
	v_lshl_add_u64 v[42:43], v[42:43], 1, s[20:21]
	v_lshl_add_u64 v[42:43], v[130:131], 1, v[42:43]
	v_cvt_pk_bf16_f32 v44, v50, v51
	s_waitcnt lgkmcnt(0)
	v_cvt_pk_bf16_f32 v45, v48, v49
	v_cvt_pk_bf16_f32 v46, v54, v55
	v_cvt_pk_bf16_f32 v47, v52, v53
	global_store_dwordx4 v[42:43], v[44:47], off sc1
	v_mov_b32_e32 v145, v144
	v_pk_mul_f32 v[36:37], v[36:37], v[144:145]
	v_mov_b32_e32 v44, v144
	v_mov_b32_e32 v45, v144
	v_pk_mul_f32 v[38:39], v[38:39], v[44:45]
	v_pk_mul_f32 v[34:35], v[34:35], v[44:45]
	v_pk_mul_f32 v[32:33], v[32:33], v[144:145]
	s_cmp_lt_i32 s43, 2
	s_mov_b64 s[38:39], -1
	s_cbranch_scc1 .LBB0_573
	s_cmp_gt_i32 s43, 2
	s_cbranch_scc0 .LBB0_570
	v_lshl_add_u64 v[44:45], v[130:131], 2, s[96:97]
	global_load_dwordx4 v[46:49], v[44:45], off offset:512
	global_load_dwordx4 v[50:53], v[44:45], off offset:528
	s_mov_b64 s[38:39], 0
	s_waitcnt vmcnt(0)
	v_pk_mul_f32 v[44:45], v[38:39], v[48:49]
	v_pk_mul_f32 v[46:47], v[36:37], v[46:47]
	v_pk_mul_f32 v[48:49], v[34:35], v[52:53]
	v_pk_mul_f32 v[50:51], v[32:33], v[50:51]

; __device__ __forceinline__ unsigned cvt_pk_bf16(float lo, float hi) { unsigned r; asm volatile("v_cvt_pk_bf16_f32 %0, %1, %2" : "=v"(r) : "v"(lo), "v"(hi)); return r; }
;     __device__ __forceinline__ void operator()(const f32x4 (&acc)[2][2][4][2], const Unit& u, int wr, int wc, int fr, int fq) const {
;     ...
;                     u32x4 w; w.x = cvt_pk_bf16(v0[0], v0[1]); w.y = cvt_pk_bf16(v0[2], v0[3]); w.z = cvt_pk_bf16(v1[0], v1[1]); w.w = cvt_pk_bf16(v1[2], v1[3]);
;                     *(u32x4*)(rowp + bj * HALF) = w;
;                 }
;                 if (do_vss) { ss += __shfl_xor(ss, 16); ss += __shfl_xor(ss, 32); if (fq == 0) vss[(size_t)row * 32 + (u.pn - 8) * 4 + wc] = ss; }
.LBB0_577:
	s_and_b64 vcc, exec, s[0:1]
	v_cvt_pk_bf16_f32 v32, v46, v47
	v_cvt_pk_bf16_f32 v33, v44, v45
	v_cvt_pk_bf16_f32 v34, v50, v51
	v_cvt_pk_bf16_f32 v35, v48, v49
	global_store_dwordx4 v[42:43], v[32:35], off offset:256 sc1
	s_cbranch_vccnz .LBB0_581
	s_nop 0
	v_and_b32_e32 v33, 64, v167
	v_xor_b32_e32 v32, 16, v167
	v_add_u32_e32 v33, 64, v33
	v_cmp_lt_i32_e32 vcc, v32, v33
	v_xor_b32_e32 v34, 32, v167
	s_nop 0
	v_cndmask_b32_e32 v32, v167, v32, vcc
	v_lshlrev_b32_e32 v32, 2, v32
	ds_bpermute_b32 v32, v32, v56
	v_cmp_lt_i32_e32 vcc, v34, v33
	s_waitcnt lgkmcnt(0)
	v_add_f32_e32 v32, v56, v32
	v_cndmask_b32_e32 v33, v167, v34, vcc
	v_lshlrev_b32_e32 v33, 2, v33
	ds_bpermute_b32 v33, v33, v32
	s_and_saveexec_b64 s[38:39], s[4:5]
	s_cbranch_execz .LBB0_580
	v_lshlrev_b64 v[34:35], 7, v[40:41]
	v_lshl_add_u64 v[34:35], s[22:23], 0, v[34:35]
	v_lshl_add_u64 v[34:35], s[36:37], 2, v[34:35]
	s_lshl_b32 s2, s53, 2
	v_lshl_add_u64 v[34:35], v[34:35], 0, s[2:3]
	s_waitcnt lgkmcnt(0)
	v_add_f32_e32 v32, v32, v33
	global_store_dword v[34:35], v32, off

; __device__ __forceinline__ unsigned cvt_pk_bf16(float lo, float hi) { unsigned r; asm volatile("v_cvt_pk_bf16_f32 %0, %1, %2" : "=v"(r) : "v"(lo), "v"(hi)); return r; }
;     __device__ __forceinline__ void operator()(const f32x4 (&acc)[2][2][4][2], const Unit& u, int wr, int wc, int fr, int fq) const {
;     ...
;                 const int row = row0 + ai * HALF + m * 16;
;                 bf16_t* rowp = O + (size_t)row * ldc + col0;
;                 float ss = 0.f;
;                 const float rs = rsv[ai * 4 + m];
; #pragma unroll
;                 for (int bj = 0; bj < 2; ++bj) {
;                     f32x4 v0 = acc[ai][bj][m][0] * rs, v1 = acc[ai][bj][m][1] * rs;
;                     if (act == ACT_GELU_VSS) {
;                         f32x2 a = gelu_pk((f32x2){v0[0], v0[1]}), b = gelu_pk((f32x2){v0[2], v0[3]}), c = gelu_pk((f32x2){v1[0], v1[1]}), d = gelu_pk((f32x2){v1[2], v1[3]});
;                         v0 = (f32x4){a.x, a.y, b.x, b.y}; v1 = (f32x4){c.x, c.y, d.x, d.y};
;                         ss += (v0[0] * v0[0] + v0[1] * v0[1]) + (v0[2] * v0[2] + v0[3] * v0[3]) + (v1[0] * v1[0] + v1[1] * v1[1]) + (v1[2] * v1[2] + v1[3] * v1[3]);
;                     } else if (act == ACT_RELU2) {
; #pragma unroll
;                         for (int j = 0; j < 4; ++j) { const float a = fmaxf(v0[j], 0.f), b = fmaxf(v1[j], 0.f); v0[j] = a * a; v1[j] = b * b; }
;                     } else if (act == ACT_COLSCALE) {
;                         v0 = v0 * *(const f32x4*)(colscale + col0 + bj * HALF); v1 = v1 * *(const f32x4*)(colscale + col0 + bj * HALF + 4);
;                     }
;                     u32x4 w; w.x = cvt_pk_bf16(v0[0], v0[1]); w.y = cvt_pk_bf16(v0[2], v0[3]); w.z = cvt_pk_bf16(v1[0], v1[1]); w.w = cvt_pk_bf16(v1[2], v1[3]);
;                     *(u32x4*)(rowp + bj * HALF) = w;
.LBB0_591:
	v_add_u32_e32 v24, 0xa0, v180
	v_mad_u64_u32 v[26:27], s[38:39], v24, s42, 0
	v_ashrrev_i32_e32 v25, 31, v24
	v_mov_b32_e32 v28, v27
	v_mad_u64_u32 v[28:29], s[38:39], v25, s42, v[28:29]
	v_mov_b32_e32 v27, v28
	v_lshl_add_u64 v[26:27], v[26:27], 1, s[20:21]
	v_lshl_add_u64 v[26:27], v[130:131], 1, v[26:27]
	v_cvt_pk_bf16_f32 v28, v34, v35
	s_waitcnt lgkmcnt(0)
	v_cvt_pk_bf16_f32 v29, v32, v33
	v_cvt_pk_bf16_f32 v30, v38, v39
	v_cvt_pk_bf16_f32 v31, v36, v37
	global_store_dwordx4 v[26:27], v[28:31], off sc1
	v_mov_b32_e32 v137, v136
	v_pk_mul_f32 v[20:21], v[20:21], v[136:137]
	v_mov_b32_e32 v28, v136
	v_mov_b32_e32 v29, v136
	v_pk_mul_f32 v[22:23], v[22:23], v[28:29]
	v_pk_mul_f32 v[18:19], v[18:19], v[28:29]
	v_pk_mul_f32 v[16:17], v[16:17], v[136:137]
	s_cmp_lt_i32 s43, 2
	s_mov_b64 s[38:39], -1
	s_cbranch_scc1 .LBB0_597
	s_cmp_gt_i32 s43, 2
	s_cbranch_scc0 .LBB0_594
	v_lshl_add_u64 v[28:29], v[130:131], 2, s[96:97]
	global_load_dwordx4 v[30:33], v[28:29], off offset:512
	global_load_dwordx4 v[34:37], v[28:29], off offset:528
	s_mov_b64 s[38:39], 0
	s_waitcnt vmcnt(0)
	v_pk_mul_f32 v[28:29], v[22:23], v[32:33]
	v_pk_mul_f32 v[30:31], v[20:21], v[30:31]
	v_pk_mul_f32 v[32:33], v[18:19], v[36:37]
	v_pk_mul_f32 v[34:35], v[16:17], v[34:35]

; __device__ __forceinline__ unsigned cvt_pk_bf16(float lo, float hi) { unsigned r; asm volatile("v_cvt_pk_bf16_f32 %0, %1, %2" : "=v"(r) : "v"(lo), "v"(hi)); return r; }
;     __device__ __forceinline__ void operator()(const f32x4 (&acc)[2][2][4][2], const Unit& u, int wr, int wc, int fr, int fq) const {
;     ...
;                     u32x4 w; w.x = cvt_pk_bf16(v0[0], v0[1]); w.y = cvt_pk_bf16(v0[2], v0[3]); w.z = cvt_pk_bf16(v1[0], v1[1]); w.w = cvt_pk_bf16(v1[2], v1[3]);
;                     *(u32x4*)(rowp + bj * HALF) = w;
;                 }
;                 if (do_vss) { ss += __shfl_xor(ss, 16); ss += __shfl_xor(ss, 32); if (fq == 0) vss[(size_t)row * 32 + (u.pn - 8) * 4 + wc] = ss; }
.LBB0_601:
	s_and_b64 vcc, exec, s[0:1]
	v_cvt_pk_bf16_f32 v16, v30, v31
	v_cvt_pk_bf16_f32 v17, v28, v29
	v_cvt_pk_bf16_f32 v18, v34, v35
	v_cvt_pk_bf16_f32 v19, v32, v33
	global_store_dwordx4 v[26:27], v[16:19], off offset:256 sc1
	s_cbranch_vccnz .LBB0_605
	s_nop 0
	v_and_b32_e32 v17, 64, v167
	v_xor_b32_e32 v16, 16, v167
	v_add_u32_e32 v17, 64, v17
	v_cmp_lt_i32_e32 vcc, v16, v17
	v_xor_b32_e32 v18, 32, v167
	s_nop 0
	v_cndmask_b32_e32 v16, v167, v16, vcc
	v_lshlrev_b32_e32 v16, 2, v16
	ds_bpermute_b32 v16, v16, v40
	v_cmp_lt_i32_e32 vcc, v18, v17
	s_waitcnt lgkmcnt(0)
	v_add_f32_e32 v16, v40, v16
	v_cndmask_b32_e32 v17, v167, v18, vcc
	v_lshlrev_b32_e32 v17, 2, v17
	ds_bpermute_b32 v17, v17, v16
	s_and_saveexec_b64 s[38:39], s[4:5]
	s_cbranch_execz .LBB0_604
	v_lshlrev_b64 v[18:19], 7, v[24:25]
	v_lshl_add_u64 v[18:19], s[22:23], 0, v[18:19]
	v_lshl_add_u64 v[18:19], s[36:37], 2, v[18:19]
	s_lshl_b32 s2, s53, 2
	v_lshl_add_u64 v[18:19], v[18:19], 0, s[2:3]
	s_waitcnt lgkmcnt(0)
	v_add_f32_e32 v16, v16, v17
	global_store_dword v[18:19], v16, off

; __device__ __forceinline__ unsigned cvt_pk_bf16(float lo, float hi) { unsigned r; asm volatile("v_cvt_pk_bf16_f32 %0, %1, %2" : "=v"(r) : "v"(lo), "v"(hi)); return r; }
;     __device__ __forceinline__ void operator()(const f32x4 (&acc)[2][2][4][2], const Unit& u, int wr, int wc, int fr, int fq) const {
;     ...
;                 const int row = row0 + ai * HALF + m * 16;
;                 bf16_t* rowp = O + (size_t)row * ldc + col0;
;                 float ss = 0.f;
;                 const float rs = rsv[ai * 4 + m];
; #pragma unroll
;                 for (int bj = 0; bj < 2; ++bj) {
;                     f32x4 v0 = acc[ai][bj][m][0] * rs, v1 = acc[ai][bj][m][1] * rs;
;                     if (act == ACT_GELU_VSS) {
;                         f32x2 a = gelu_pk((f32x2){v0[0], v0[1]}), b = gelu_pk((f32x2){v0[2], v0[3]}), c = gelu_pk((f32x2){v1[0], v1[1]}), d = gelu_pk((f32x2){v1[2], v1[3]});
;                         v0 = (f32x4){a.x, a.y, b.x, b.y}; v1 = (f32x4){c.x, c.y, d.x, d.y};
;                         ss += (v0[0] * v0[0] + v0[1] * v0[1]) + (v0[2] * v0[2] + v0[3] * v0[3]) + (v1[0] * v1[0] + v1[1] * v1[1]) + (v1[2] * v1[2] + v1[3] * v1[3]);
;                     } else if (act == ACT_RELU2) {
; #pragma unroll
;                         for (int j = 0; j < 4; ++j) { const float a = fmaxf(v0[j], 0.f), b = fmaxf(v1[j], 0.f); v0[j] = a * a; v1[j] = b * b; }
;                     } else if (act == ACT_COLSCALE) {
;                         v0 = v0 * *(const f32x4*)(colscale + col0 + bj * HALF); v1 = v1 * *(const f32x4*)(colscale + col0 + bj * HALF + 4);
;                     }
;                     u32x4 w; w.x = cvt_pk_bf16(v0[0], v0[1]); w.y = cvt_pk_bf16(v0[2], v0[3]); w.z = cvt_pk_bf16(v1[0], v1[1]); w.w = cvt_pk_bf16(v1[2], v1[3]);
;                     *(u32x4*)(rowp + bj * HALF) = w;
.LBB0_615:
	v_add_u32_e32 v8, 0xb0, v180
	v_mad_u64_u32 v[10:11], s[38:39], v8, s42, 0
	v_ashrrev_i32_e32 v9, 31, v8
	v_mov_b32_e32 v12, v11
	v_mad_u64_u32 v[12:13], s[38:39], v9, s42, v[12:13]
	v_mov_b32_e32 v11, v12
	v_lshl_add_u64 v[10:11], v[10:11], 1, s[20:21]
	v_lshl_add_u64 v[10:11], v[130:131], 1, v[10:11]
	v_cvt_pk_bf16_f32 v12, v18, v19
	s_waitcnt lgkmcnt(0)
	v_cvt_pk_bf16_f32 v13, v16, v17
	v_cvt_pk_bf16_f32 v14, v22, v23
	v_cvt_pk_bf16_f32 v15, v20, v21
	global_store_dwordx4 v[10:11], v[12:15], off sc1
	v_mov_b32_e32 v129, v128
	v_pk_mul_f32 v[4:5], v[4:5], v[128:129]
	v_mov_b32_e32 v12, v128
	v_mov_b32_e32 v13, v128
	v_pk_mul_f32 v[6:7], v[6:7], v[12:13]
	v_pk_mul_f32 v[2:3], v[2:3], v[12:13]
	v_pk_mul_f32 v[0:1], v[0:1], v[128:129]
	s_cmp_lt_i32 s43, 2
	s_mov_b64 s[38:39], -1
	s_cbranch_scc1 .LBB0_621
	s_cmp_gt_i32 s43, 2
	s_cbranch_scc0 .LBB0_618
	v_lshl_add_u64 v[12:13], v[130:131], 2, s[96:97]
	global_load_dwordx4 v[14:17], v[12:13], off offset:512
	global_load_dwordx4 v[18:21], v[12:13], off offset:528
	s_mov_b64 s[38:39], 0
	s_waitcnt vmcnt(0)
	v_pk_mul_f32 v[12:13], v[6:7], v[16:17]
	v_pk_mul_f32 v[14:15], v[4:5], v[14:15]
	v_pk_mul_f32 v[16:17], v[2:3], v[20:21]
	v_pk_mul_f32 v[18:19], v[0:1], v[18:19]

; __device__ __forceinline__ unsigned cvt_pk_bf16(float lo, float hi) { unsigned r; asm volatile("v_cvt_pk_bf16_f32 %0, %1, %2" : "=v"(r) : "v"(lo), "v"(hi)); return r; }
;     __device__ __forceinline__ void operator()(const f32x4 (&acc)[2][2][4][2], const Unit& u, int wr, int wc, int fr, int fq) const {
;     ...
;                     u32x4 w; w.x = cvt_pk_bf16(v0[0], v0[1]); w.y = cvt_pk_bf16(v0[2], v0[3]); w.z = cvt_pk_bf16(v1[0], v1[1]); w.w = cvt_pk_bf16(v1[2], v1[3]);
;                     *(u32x4*)(rowp + bj * HALF) = w;
;                 }
;                 if (do_vss) { ss += __shfl_xor(ss, 16); ss += __shfl_xor(ss, 32); if (fq == 0) vss[(size_t)row * 32 + (u.pn - 8) * 4 + wc] = ss; }
.LBB0_625:
	s_and_b64 vcc, exec, s[0:1]
	v_cvt_pk_bf16_f32 v0, v14, v15
	v_cvt_pk_bf16_f32 v1, v12, v13
	v_cvt_pk_bf16_f32 v2, v18, v19
	v_cvt_pk_bf16_f32 v3, v16, v17
	global_store_dwordx4 v[10:11], v[0:3], off offset:256 sc1
	s_cbranch_vccnz .LBB0_629
	s_nop 0
	v_and_b32_e32 v1, 64, v167
	v_xor_b32_e32 v0, 16, v167
	v_add_u32_e32 v1, 64, v1
	v_cmp_lt_i32_e32 vcc, v0, v1
	v_xor_b32_e32 v2, 32, v167
	s_nop 0
	v_cndmask_b32_e32 v0, v167, v0, vcc
	v_lshlrev_b32_e32 v0, 2, v0
	ds_bpermute_b32 v0, v0, v24
	v_cmp_lt_i32_e32 vcc, v2, v1
	s_waitcnt lgkmcnt(0)
	v_add_f32_e32 v0, v24, v0
	v_cndmask_b32_e32 v1, v167, v2, vcc
	v_lshlrev_b32_e32 v1, 2, v1
	ds_bpermute_b32 v1, v1, v0
	s_and_saveexec_b64 s[0:1], s[4:5]
	s_cbranch_execz .LBB0_628
	v_lshlrev_b64 v[2:3], 7, v[8:9]
	v_lshl_add_u64 v[2:3], s[22:23], 0, v[2:3]
	v_lshl_add_u64 v[2:3], s[36:37], 2, v[2:3]
	s_lshl_b32 s2, s53, 2
	v_lshl_add_u64 v[2:3], v[2:3], 0, s[2:3]
	s_waitcnt lgkmcnt(0)
	v_add_f32_e32 v0, v0, v1
	global_store_dword v[2:3], v0, off
